# tight M-phase handoff: priority raised before the end-of-R barrier and the redundant post-barrier lgkmcnt wait removed, so the first MFMA follows the barrier directly (on top of early end-of-M barrier
# baseline (speedup 1.0000x reference)
; #define PG8_STAGE(bufoff, gbase, voff) do { _Pragma("unroll") for (int _i = 0; _i < 2; ++_i) \
;         __builtin_amdgcn_global_load_lds((const unsigned*)((const char*)(gbase) + (voff)[_i]), (LAS unsigned*)(lds + (bufoff) + ldsw + _i * 8192), 16, 0, 0); } while (0)
; #define PG8_LDA(dst, b, h) do { _Pragma("unroll") for (int m = 0; m < 4; ++m) _Pragma("unroll") for (int k = 0; k < 2; ++k) dst[m][k] = *(const LAS bf16x8*)(lds + PG8_SA(b, h) + aoff + m * 2048 + k * 1024); } while (0)
; #define PG8_LDB(dst, b, h) do { _Pragma("unroll") for (int n = 0; n < 2; ++n) _Pragma("unroll") for (int k = 0; k < 2; ++k) dst[n][k] = *(const LAS bf16x8*)(lds + PG8_SB(b, h) + boff + n * 2048 + k * 1024); } while (0)
; #define PG8_MMA(ai, bj, At, Bt) do { __builtin_amdgcn_s_setprio(3); _Pragma("unroll") for (int m = 0; m < 4; ++m) _Pragma("unroll") for (int n = 0; n < 2; ++n) _Pragma("unroll") for (int k = 0; k < 2; ++k) \
;         acc[ai][bj][m][n] = __builtin_amdgcn_mfma_f32_16x16x32_bf16(Bt[n][k], At[m][k], acc[ai][bj][m][n], 0, 0, 0); __builtin_amdgcn_s_setprio(0); } while (0)
; #define PG8_WAIT_V(n) asm volatile("s_waitcnt vmcnt(" #n ")" ::: "memory")
; #define PG8_WAIT_L(n) asm volatile("s_waitcnt lgkmcnt(" #n ")" ::: "memory")
; #define PG8_BAR __builtin_amdgcn_s_barrier()
; template <class Epi, class Sched, bool ALIGN_EPI = false, bool SP2 = false>
; __device__ __forceinline__ void gemm_phase(LAS unsigned char* lds, const Gemm g, const Sched& S, const Epi& E) {
;     ...
;             const char* a2 = last ? nA : cA + (size_t)(t + 2) * kstep; const char* b2 = last ? nB : cB + (size_t)(t + 2) * kstep;
;             const char* a3 = a2 + kstep; const char* b3 = b2 + kstep;
;             if (last && has_next) S.a_ready(nxt);
;             if constexpr (Epi::MID) { if (t == nt / 2) E.mid(acc, cur, wr, wc, fr, fq); }
;             if constexpr (SP2) {
;             PG8_LDB(B0, 0, 0); PG8_LDB(B1, 0, 1); PG8_SCHED; PG8_LDA(At, 0, 0); PG8_STAGE(PG8_SA(1, 1), a1 + hsA, voffA);
;             PG8_WAIT_V(8); PG8_WAIT_L(0); PG8_BAR; PG8_MMA(0, 0, At, B0); PG8_MMA(0, 1, At, B1); PG8_BAR; PG8_SCHED;
;             PG8_LDA(At, 0, 1); PG8_STAGE(PG8_SB(0, 0), b2, voffB); PG8_STAGE(PG8_SB(0, 1), b2 + hsB, voffB); PG8_STAGE(PG8_SA(0, 0), a2, voffA);
;             PG8_WAIT_V(8); PG8_WAIT_L(0); PG8_BAR; PG8_MMA(1, 0, At, B0); PG8_MMA(1, 1, At, B1); PG8_BAR; PG8_SCHED;
.LBB0_64:
	ds_read_b128 v[128:131], v158
	ds_read_b128 v[150:153], v251
	ds_read_b128 v[166:169], v158 offset:2048
	ds_read_b128 v[170:173], v251 offset:2048
	ds_read_b128 v[174:177], v159
	ds_read_b128 v[178:181], v252
	ds_read_b128 v[182:185], v159 offset:2048
	ds_read_b128 v[186:189], v252 offset:2048
	s_add_u32 s6, s4, 0xffefc080
	s_addc_u32 s7, s5, -1
	s_cmp_eq_u32 s91, 60
	s_cselect_b32 s63, s59, s7
	s_cselect_b32 s62, s58, s6
	s_cselect_b32 s7, s61, s90
	s_cselect_b32 s6, s60, s89
	s_sub_u32 s100, s4, 0x104000
	s_subb_u32 s101, s5, 0
	v_lshl_add_u64 v[242:243], s[100:101], 0, v[132:133]
	s_mov_b32 m0, s76
	v_lshl_add_u64 v[244:245], s[100:101], 0, v[136:137]
	global_load_lds_dwordx4 v[242:243], off
	s_mov_b32 m0, s77
	s_nop 0
	global_load_lds_dwordx4 v[244:245], off
	v_lshl_add_u64 v[226:227], s[4:5], 0, v[142:143]
	s_add_i32 m0, s68, 0xc000
	ds_read_b128 v[190:193], v160
	ds_read_b128 v[194:197], v250
	ds_read_b128 v[198:201], v160 offset:2048
	ds_read_b128 v[206:209], v250 offset:2048
	ds_read_b128 v[210:213], v160 offset:4096
	ds_read_b128 v[214:217], v250 offset:4096
	ds_read_b128 v[218:221], v160 offset:6144
	ds_read_b128 v[222:225], v250 offset:6144
	global_load_lds_dwordx4 v[226:227], off
	v_lshl_add_u64 v[226:227], s[4:5], 0, v[144:145]
	s_add_i32 m0, s68, 0xe000
	s_nop 0
	global_load_lds_dwordx4 v[226:227], off
	s_waitcnt vmcnt(8)
	s_waitcnt lgkmcnt(0)
	s_setprio 2
	s_barrier
	v_mfma_f32_16x16x32_bf16 v[124:127], v[128:131], v[190:193], v[124:127]
	v_mfma_f32_16x16x32_bf16 v[124:127], v[150:153], v[194:197], v[124:127]
	v_mfma_f32_16x16x32_bf16 v[120:123], v[166:169], v[190:193], v[120:123]
	v_mfma_f32_16x16x32_bf16 v[120:123], v[170:173], v[194:197], v[120:123]
	v_mfma_f32_16x16x32_bf16 v[108:111], v[128:131], v[198:201], v[108:111]
	v_mfma_f32_16x16x32_bf16 v[108:111], v[150:153], v[206:209], v[108:111]
	v_mfma_f32_16x16x32_bf16 v[104:107], v[166:169], v[198:201], v[104:107]
	v_mfma_f32_16x16x32_bf16 v[104:107], v[170:173], v[206:209], v[104:107]
	v_mfma_f32_16x16x32_bf16 v[92:95], v[128:131], v[210:213], v[92:95]
	v_mfma_f32_16x16x32_bf16 v[92:95], v[150:153], v[214:217], v[92:95]
	v_mfma_f32_16x16x32_bf16 v[88:91], v[166:169], v[210:213], v[88:91]
	v_mfma_f32_16x16x32_bf16 v[88:91], v[170:173], v[214:217], v[88:91]
	v_mfma_f32_16x16x32_bf16 v[76:79], v[128:131], v[218:221], v[76:79]
	v_mfma_f32_16x16x32_bf16 v[76:79], v[150:153], v[222:225], v[76:79]
	v_mfma_f32_16x16x32_bf16 v[72:75], v[166:169], v[218:221], v[72:75]
	v_mfma_f32_16x16x32_bf16 v[72:75], v[170:173], v[222:225], v[72:75]
	s_setprio 0
	s_setprio 2
	v_mfma_f32_16x16x32_bf16 v[116:119], v[174:177], v[190:193], v[116:119]
	v_mfma_f32_16x16x32_bf16 v[116:119], v[178:181], v[194:197], v[116:119]
	v_mfma_f32_16x16x32_bf16 v[112:115], v[182:185], v[190:193], v[112:115]
	v_mfma_f32_16x16x32_bf16 v[112:115], v[186:189], v[194:197], v[112:115]
	v_mfma_f32_16x16x32_bf16 v[100:103], v[174:177], v[198:201], v[100:103]
	v_mfma_f32_16x16x32_bf16 v[100:103], v[178:181], v[206:209], v[100:103]
	v_mfma_f32_16x16x32_bf16 v[96:99], v[182:185], v[198:201], v[96:99]
	v_mfma_f32_16x16x32_bf16 v[96:99], v[186:189], v[206:209], v[96:99]
	v_mfma_f32_16x16x32_bf16 v[84:87], v[174:177], v[210:213], v[84:87]
	v_mfma_f32_16x16x32_bf16 v[84:87], v[178:181], v[214:217], v[84:87]
	v_mfma_f32_16x16x32_bf16 v[80:83], v[182:185], v[210:213], v[80:83]
	v_mfma_f32_16x16x32_bf16 v[80:83], v[186:189], v[214:217], v[80:83]
	v_mfma_f32_16x16x32_bf16 v[68:71], v[174:177], v[218:221], v[68:71]
	v_mfma_f32_16x16x32_bf16 v[68:71], v[178:181], v[222:225], v[68:71]
	v_mfma_f32_16x16x32_bf16 v[64:67], v[182:185], v[218:221], v[64:67]
	s_setprio 3
	s_barrier
	v_mfma_f32_16x16x32_bf16 v[64:67], v[186:189], v[222:225], v[64:67]
	s_setprio 0
	s_add_i32 s92, s82, s67
	v_lshl_add_u64 v[226:227], s[6:7], 0, v[134:135]
	s_mov_b32 m0, s92
	ds_read_b128 v[190:193], v160 offset:16384
	ds_read_b128 v[194:197], v250 offset:16384
	ds_read_b128 v[198:201], v160 offset:18432
	ds_read_b128 v[206:209], v250 offset:18432
	ds_read_b128 v[210:213], v160 offset:20480
	ds_read_b128 v[214:217], v250 offset:20480
	ds_read_b128 v[218:221], v160 offset:22528
	ds_read_b128 v[222:225], v250 offset:22528
	global_load_lds_dwordx4 v[226:227], off
	s_add_i32 m0, s92, 0x2000
	s_add_u32 s92, s6, 0x41000
	v_lshl_add_u64 v[228:229], s[6:7], 0, v[138:139]
	s_addc_u32 s93, s7, 0
	s_add_i32 s94, s83, s67
	global_load_lds_dwordx4 v[228:229], off
	v_lshl_add_u64 v[230:231], s[92:93], 0, v[134:135]
	s_mov_b32 m0, s94
	s_nop 0
	global_load_lds_dwordx4 v[230:231], off
	v_lshl_add_u64 v[230:231], s[92:93], 0, v[138:139]
	s_add_i32 m0, s94, 0x2000
	s_nop 0
	global_load_lds_dwordx4 v[230:231], off
	s_waitcnt vmcnt(6)
	s_waitcnt lgkmcnt(0)
	s_setprio 2
	s_barrier
; #define PG8_STAGE(bufoff, gbase, voff) do { _Pragma("unroll") for (int _i = 0; _i < 2; ++_i) \
;         __builtin_amdgcn_global_load_lds((const unsigned*)((const char*)(gbase) + (voff)[_i]), (LAS unsigned*)(lds + (bufoff) + ldsw + _i * 8192), 16, 0, 0); } while (0)
; #define PG8_LDA(dst, b, h) do { _Pragma("unroll") for (int m = 0; m < 4; ++m) _Pragma("unroll") for (int k = 0; k < 2; ++k) dst[m][k] = *(const LAS bf16x8*)(lds + PG8_SA(b, h) + aoff + m * 2048 + k * 1024); } while (0)
; #define PG8_LDB(dst, b, h) do { _Pragma("unroll") for (int n = 0; n < 2; ++n) _Pragma("unroll") for (int k = 0; k < 2; ++k) dst[n][k] = *(const LAS bf16x8*)(lds + PG8_SB(b, h) + boff + n * 2048 + k * 1024); } while (0)
; #define PG8_MMA(ai, bj, At, Bt) do { __builtin_amdgcn_s_setprio(3); _Pragma("unroll") for (int m = 0; m < 4; ++m) _Pragma("unroll") for (int n = 0; n < 2; ++n) _Pragma("unroll") for (int k = 0; k < 2; ++k) \
;         acc[ai][bj][m][n] = __builtin_amdgcn_mfma_f32_16x16x32_bf16(Bt[n][k], At[m][k], acc[ai][bj][m][n], 0, 0, 0); __builtin_amdgcn_s_setprio(0); } while (0)
; #define PG8_WAIT_V(n) asm volatile("s_waitcnt vmcnt(" #n ")" ::: "memory")
; #define PG8_WAIT_L(n) asm volatile("s_waitcnt lgkmcnt(" #n ")" ::: "memory")
; #define PG8_BAR __builtin_amdgcn_s_barrier()
; #define PG8_SCHED __builtin_amdgcn_sched_barrier(0)
; template <class Epi, class Sched, bool ALIGN_EPI = false, bool SP2 = false>
; __device__ __forceinline__ void gemm_phase(LAS unsigned char* lds, const Gemm g, const Sched& S, const Epi& E) {
;     ...
;             PG8_WAIT_V(8); PG8_WAIT_L(0); PG8_BAR; PG8_MMA(1, 0, At, B0); PG8_MMA(1, 1, At, B1); PG8_BAR; PG8_SCHED;
;             PG8_LDB(B0, 1, 0); PG8_LDB(B1, 1, 1); PG8_SCHED; PG8_LDA(At, 1, 0); PG8_STAGE(PG8_SA(0, 1), a2 + hsA, voffA);
;             PG8_WAIT_V(8); PG8_WAIT_L(0); PG8_BAR; PG8_MMA(0, 0, At, B0); PG8_MMA(0, 1, At, B1); PG8_BAR; PG8_SCHED;
	v_mfma_f32_16x16x32_bf16 v[60:63], v[128:131], v[190:193], v[60:63]
	v_mfma_f32_16x16x32_bf16 v[60:63], v[150:153], v[194:197], v[60:63]
	v_mfma_f32_16x16x32_bf16 v[56:59], v[166:169], v[190:193], v[56:59]
	v_mfma_f32_16x16x32_bf16 v[56:59], v[170:173], v[194:197], v[56:59]
	v_mfma_f32_16x16x32_bf16 v[44:47], v[128:131], v[198:201], v[44:47]
	v_mfma_f32_16x16x32_bf16 v[44:47], v[150:153], v[206:209], v[44:47]
	v_mfma_f32_16x16x32_bf16 v[40:43], v[166:169], v[198:201], v[40:43]
	v_mfma_f32_16x16x32_bf16 v[40:43], v[170:173], v[206:209], v[40:43]
	v_mfma_f32_16x16x32_bf16 v[28:31], v[128:131], v[210:213], v[28:31]
	v_mfma_f32_16x16x32_bf16 v[28:31], v[150:153], v[214:217], v[28:31]
	v_mfma_f32_16x16x32_bf16 v[24:27], v[166:169], v[210:213], v[24:27]
	v_mfma_f32_16x16x32_bf16 v[24:27], v[170:173], v[214:217], v[24:27]
	v_mfma_f32_16x16x32_bf16 v[12:15], v[128:131], v[218:221], v[12:15]
	v_mfma_f32_16x16x32_bf16 v[12:15], v[150:153], v[222:225], v[12:15]
	v_mfma_f32_16x16x32_bf16 v[8:11], v[166:169], v[218:221], v[8:11]
	v_mfma_f32_16x16x32_bf16 v[8:11], v[170:173], v[222:225], v[8:11]
	s_setprio 0
	s_setprio 2
	v_mfma_f32_16x16x32_bf16 v[52:55], v[174:177], v[190:193], v[52:55]
	v_mfma_f32_16x16x32_bf16 v[52:55], v[178:181], v[194:197], v[52:55]
	v_mfma_f32_16x16x32_bf16 v[48:51], v[182:185], v[190:193], v[48:51]
	v_mfma_f32_16x16x32_bf16 v[48:51], v[186:189], v[194:197], v[48:51]
	v_mfma_f32_16x16x32_bf16 v[36:39], v[174:177], v[198:201], v[36:39]
	v_mfma_f32_16x16x32_bf16 v[36:39], v[178:181], v[206:209], v[36:39]
	v_mfma_f32_16x16x32_bf16 v[32:35], v[182:185], v[198:201], v[32:35]
	v_mfma_f32_16x16x32_bf16 v[32:35], v[186:189], v[206:209], v[32:35]
	v_mfma_f32_16x16x32_bf16 v[20:23], v[174:177], v[210:213], v[20:23]
	v_mfma_f32_16x16x32_bf16 v[20:23], v[178:181], v[214:217], v[20:23]
	v_mfma_f32_16x16x32_bf16 v[16:19], v[182:185], v[210:213], v[16:19]
	v_mfma_f32_16x16x32_bf16 v[16:19], v[186:189], v[214:217], v[16:19]
	v_mfma_f32_16x16x32_bf16 v[4:7], v[174:177], v[218:221], v[4:7]
	v_mfma_f32_16x16x32_bf16 v[4:7], v[178:181], v[222:225], v[4:7]
	v_mfma_f32_16x16x32_bf16 v[0:3], v[182:185], v[218:221], v[0:3]
	s_setprio 3
	s_barrier
	v_mfma_f32_16x16x32_bf16 v[0:3], v[186:189], v[222:225], v[0:3]
	s_setprio 0
	s_add_i32 s92, 0, 0x18000
	v_add_u32_e32 v165, s92, v156
	v_xor_b32_e32 v253, 64, v165
	s_add_i32 s93, 0, 0x1c000
	ds_read_b128 v[128:131], v165
	ds_read_b128 v[150:153], v253
	ds_read_b128 v[166:169], v165 offset:2048
	ds_read_b128 v[170:173], v253 offset:2048
	v_add_u32_e32 v165, s93, v156
	v_xor_b32_e32 v253, 64, v165
	ds_read_b128 v[174:177], v165
	ds_read_b128 v[178:181], v253
	ds_read_b128 v[182:185], v165 offset:2048
	ds_read_b128 v[186:189], v253 offset:2048
	v_lshl_add_u64 v[242:243], s[62:63], 0, v[132:133]
	s_mov_b32 m0, s68
	v_lshl_add_u64 v[244:245], s[62:63], 0, v[136:137]
	global_load_lds_dwordx4 v[242:243], off
	s_mov_b32 m0, s69
	s_nop 0
	global_load_lds_dwordx4 v[244:245], off
	s_add_u32 s62, s62, 0x104000
	s_addc_u32 s63, s63, 0
	s_mov_b32 m0, s70
	v_lshl_add_u64 v[234:235], s[62:63], 0, v[132:133]
	ds_read_b128 v[190:193], v160 offset:32768
	ds_read_b128 v[194:197], v250 offset:32768
	ds_read_b128 v[198:201], v160 offset:34816
	ds_read_b128 v[206:209], v250 offset:34816
	ds_read_b128 v[210:213], v160 offset:36864
	ds_read_b128 v[214:217], v250 offset:36864
	ds_read_b128 v[218:221], v160 offset:38912
	ds_read_b128 v[222:225], v250 offset:38912
	global_load_lds_dwordx4 v[234:235], off
	v_lshl_add_u64 v[234:235], s[62:63], 0, v[136:137]
	s_mov_b32 m0, s71
	s_nop 0
	global_load_lds_dwordx4 v[234:235], off
	s_waitcnt vmcnt(8)
	s_waitcnt lgkmcnt(0)
	s_setprio 2
	s_barrier
; #define PG8_STAGE(bufoff, gbase, voff) do { _Pragma("unroll") for (int _i = 0; _i < 2; ++_i) \
;         __builtin_amdgcn_global_load_lds((const unsigned*)((const char*)(gbase) + (voff)[_i]), (LAS unsigned*)(lds + (bufoff) + ldsw + _i * 8192), 16, 0, 0); } while (0)
; #define PG8_LDA(dst, b, h) do { _Pragma("unroll") for (int m = 0; m < 4; ++m) _Pragma("unroll") for (int k = 0; k < 2; ++k) dst[m][k] = *(const LAS bf16x8*)(lds + PG8_SA(b, h) + aoff + m * 2048 + k * 1024); } while (0)
; #define PG8_MMA(ai, bj, At, Bt) do { __builtin_amdgcn_s_setprio(3); _Pragma("unroll") for (int m = 0; m < 4; ++m) _Pragma("unroll") for (int n = 0; n < 2; ++n) _Pragma("unroll") for (int k = 0; k < 2; ++k) \
;         acc[ai][bj][m][n] = __builtin_amdgcn_mfma_f32_16x16x32_bf16(Bt[n][k], At[m][k], acc[ai][bj][m][n], 0, 0, 0); __builtin_amdgcn_s_setprio(0); } while (0)
; #define PG8_WAIT_V(n) asm volatile("s_waitcnt vmcnt(" #n ")" ::: "memory")
; #define PG8_WAIT_L(n) asm volatile("s_waitcnt lgkmcnt(" #n ")" ::: "memory")
; #define PG8_BAR __builtin_amdgcn_s_barrier()
; #define PG8_SCHED __builtin_amdgcn_sched_barrier(0)
; template <class Epi, class Sched, bool ALIGN_EPI = false, bool SP2 = false>
; __device__ __forceinline__ void gemm_phase(LAS unsigned char* lds, const Gemm g, const Sched& S, const Epi& E) {
;     ...
;             PG8_WAIT_V(8); PG8_WAIT_L(0); PG8_BAR; PG8_MMA(0, 0, At, B0); PG8_MMA(0, 1, At, B1); PG8_BAR; PG8_SCHED;
;             PG8_LDA(At, 1, 1); PG8_STAGE(PG8_SB(1, 0), b3, voffB); PG8_STAGE(PG8_SB(1, 1), b3 + hsB, voffB); PG8_STAGE(PG8_SA(1, 0), a3, voffA);
;             PG8_WAIT_V(8); PG8_WAIT_L(0); PG8_BAR; PG8_MMA(1, 0, At, B0); PG8_MMA(1, 1, At, B1); PG8_BAR; PG8_SCHED;
	v_mfma_f32_16x16x32_bf16 v[124:127], v[128:131], v[190:193], v[124:127]
	v_mfma_f32_16x16x32_bf16 v[124:127], v[150:153], v[194:197], v[124:127]
	v_mfma_f32_16x16x32_bf16 v[120:123], v[166:169], v[190:193], v[120:123]
	v_mfma_f32_16x16x32_bf16 v[120:123], v[170:173], v[194:197], v[120:123]
	v_mfma_f32_16x16x32_bf16 v[108:111], v[128:131], v[198:201], v[108:111]
	v_mfma_f32_16x16x32_bf16 v[108:111], v[150:153], v[206:209], v[108:111]
	v_mfma_f32_16x16x32_bf16 v[104:107], v[166:169], v[198:201], v[104:107]
	v_mfma_f32_16x16x32_bf16 v[104:107], v[170:173], v[206:209], v[104:107]
	v_mfma_f32_16x16x32_bf16 v[92:95], v[128:131], v[210:213], v[92:95]
	v_mfma_f32_16x16x32_bf16 v[92:95], v[150:153], v[214:217], v[92:95]
	v_mfma_f32_16x16x32_bf16 v[88:91], v[166:169], v[210:213], v[88:91]
	v_mfma_f32_16x16x32_bf16 v[88:91], v[170:173], v[214:217], v[88:91]
	v_mfma_f32_16x16x32_bf16 v[76:79], v[128:131], v[218:221], v[76:79]
	v_mfma_f32_16x16x32_bf16 v[76:79], v[150:153], v[222:225], v[76:79]
	v_mfma_f32_16x16x32_bf16 v[72:75], v[166:169], v[218:221], v[72:75]
	v_mfma_f32_16x16x32_bf16 v[72:75], v[170:173], v[222:225], v[72:75]
	s_setprio 0
	s_setprio 2
	v_mfma_f32_16x16x32_bf16 v[116:119], v[174:177], v[190:193], v[116:119]
	v_mfma_f32_16x16x32_bf16 v[116:119], v[178:181], v[194:197], v[116:119]
	v_mfma_f32_16x16x32_bf16 v[112:115], v[182:185], v[190:193], v[112:115]
	v_mfma_f32_16x16x32_bf16 v[112:115], v[186:189], v[194:197], v[112:115]
	v_mfma_f32_16x16x32_bf16 v[100:103], v[174:177], v[198:201], v[100:103]
	v_mfma_f32_16x16x32_bf16 v[100:103], v[178:181], v[206:209], v[100:103]
	v_mfma_f32_16x16x32_bf16 v[96:99], v[182:185], v[198:201], v[96:99]
	v_mfma_f32_16x16x32_bf16 v[96:99], v[186:189], v[206:209], v[96:99]
	v_mfma_f32_16x16x32_bf16 v[84:87], v[174:177], v[210:213], v[84:87]
	v_mfma_f32_16x16x32_bf16 v[84:87], v[178:181], v[214:217], v[84:87]
	v_mfma_f32_16x16x32_bf16 v[80:83], v[182:185], v[210:213], v[80:83]
	v_mfma_f32_16x16x32_bf16 v[80:83], v[186:189], v[214:217], v[80:83]
	v_mfma_f32_16x16x32_bf16 v[68:71], v[174:177], v[218:221], v[68:71]
	v_mfma_f32_16x16x32_bf16 v[68:71], v[178:181], v[222:225], v[68:71]
	v_mfma_f32_16x16x32_bf16 v[64:67], v[182:185], v[218:221], v[64:67]
	s_setprio 3
	s_barrier
	v_mfma_f32_16x16x32_bf16 v[64:67], v[186:189], v[222:225], v[64:67]
	s_setprio 0
	s_add_i32 s62, s92, s67
	v_lshl_add_u64 v[226:227], v[226:227], 0, s[46:47]
	s_mov_b32 m0, s62
	ds_read_b128 v[190:193], v160 offset:49152
	ds_read_b128 v[194:197], v250 offset:49152
	ds_read_b128 v[198:201], v160 offset:51200
	ds_read_b128 v[206:209], v250 offset:51200
	ds_read_b128 v[210:213], v160 offset:53248
	ds_read_b128 v[214:217], v250 offset:53248
	ds_read_b128 v[218:221], v160 offset:55296
	ds_read_b128 v[222:225], v250 offset:55296
	global_load_lds_dwordx4 v[226:227], off
	s_add_i32 m0, s62, 0x2000
	s_add_u32 s6, s6, 0x41080
	v_lshl_add_u64 v[226:227], v[228:229], 0, s[46:47]
	s_addc_u32 s7, s7, 0
	s_add_i32 s62, s93, s67
	global_load_lds_dwordx4 v[226:227], off
	v_lshl_add_u64 v[226:227], s[6:7], 0, v[134:135]
	s_mov_b32 m0, s62
	s_nop 0
	global_load_lds_dwordx4 v[226:227], off
	v_lshl_add_u64 v[226:227], s[6:7], 0, v[138:139]
	s_add_i32 m0, s62, 0x2000
	s_nop 0
	global_load_lds_dwordx4 v[226:227], off
	s_waitcnt vmcnt(6)
	s_waitcnt lgkmcnt(0)
	s_setprio 2
	s_barrier
	v_mfma_f32_16x16x32_bf16 v[60:63], v[128:131], v[190:193], v[60:63]
	v_mfma_f32_16x16x32_bf16 v[60:63], v[150:153], v[194:197], v[60:63]
	v_mfma_f32_16x16x32_bf16 v[56:59], v[166:169], v[190:193], v[56:59]
	v_mfma_f32_16x16x32_bf16 v[56:59], v[170:173], v[194:197], v[56:59]
	v_mfma_f32_16x16x32_bf16 v[44:47], v[128:131], v[198:201], v[44:47]
	v_mfma_f32_16x16x32_bf16 v[44:47], v[150:153], v[206:209], v[44:47]
	v_mfma_f32_16x16x32_bf16 v[40:43], v[166:169], v[198:201], v[40:43]
	v_mfma_f32_16x16x32_bf16 v[40:43], v[170:173], v[206:209], v[40:43]
	v_mfma_f32_16x16x32_bf16 v[28:31], v[128:131], v[210:213], v[28:31]
	v_mfma_f32_16x16x32_bf16 v[28:31], v[150:153], v[214:217], v[28:31]
	v_mfma_f32_16x16x32_bf16 v[24:27], v[166:169], v[210:213], v[24:27]
	v_mfma_f32_16x16x32_bf16 v[24:27], v[170:173], v[214:217], v[24:27]
	v_mfma_f32_16x16x32_bf16 v[12:15], v[128:131], v[218:221], v[12:15]
	v_mfma_f32_16x16x32_bf16 v[12:15], v[150:153], v[222:225], v[12:15]
	v_mfma_f32_16x16x32_bf16 v[8:11], v[166:169], v[218:221], v[8:11]
	v_mfma_f32_16x16x32_bf16 v[8:11], v[170:173], v[222:225], v[8:11]
	s_setprio 0
	s_setprio 2
	v_mfma_f32_16x16x32_bf16 v[52:55], v[174:177], v[190:193], v[52:55]
	v_mfma_f32_16x16x32_bf16 v[52:55], v[178:181], v[194:197], v[52:55]
	v_mfma_f32_16x16x32_bf16 v[48:51], v[182:185], v[190:193], v[48:51]
	v_mfma_f32_16x16x32_bf16 v[48:51], v[186:189], v[194:197], v[48:51]
	v_mfma_f32_16x16x32_bf16 v[36:39], v[174:177], v[198:201], v[36:39]
	v_mfma_f32_16x16x32_bf16 v[36:39], v[178:181], v[206:209], v[36:39]
	v_mfma_f32_16x16x32_bf16 v[32:35], v[182:185], v[198:201], v[32:35]
	v_mfma_f32_16x16x32_bf16 v[32:35], v[186:189], v[206:209], v[32:35]
	v_mfma_f32_16x16x32_bf16 v[20:23], v[174:177], v[210:213], v[20:23]
	v_mfma_f32_16x16x32_bf16 v[20:23], v[178:181], v[214:217], v[20:23]
	v_mfma_f32_16x16x32_bf16 v[16:19], v[182:185], v[210:213], v[16:19]
	v_mfma_f32_16x16x32_bf16 v[16:19], v[186:189], v[214:217], v[16:19]
	v_mfma_f32_16x16x32_bf16 v[4:7], v[174:177], v[218:221], v[4:7]
	v_mfma_f32_16x16x32_bf16 v[4:7], v[178:181], v[222:225], v[4:7]
	v_mfma_f32_16x16x32_bf16 v[0:3], v[182:185], v[218:221], v[0:3]
	s_setprio 3
	s_barrier
	v_mfma_f32_16x16x32_bf16 v[0:3], v[186:189], v[222:225], v[0:3]
	s_setprio 0
	s_add_i32 s91, s91, 2
	s_add_u32 s4, s4, 0x100
	s_addc_u32 s5, s5, 0
	s_add_u32 s89, s89, 0x100
	s_addc_u32 s90, s90, 0
	s_cmp_gt_u32 s91, 61
	s_cbranch_scc0 .LBB0_64
	s_and_b64 vcc, exec, s[50:51]
	s_cbranch_vccz .LBB0_67
	s_barrier

; #define PG8_STAGE(bufoff, gbase, voff) do { _Pragma("unroll") for (int _i = 0; _i < 2; ++_i) \
;         __builtin_amdgcn_global_load_lds((const unsigned*)((const char*)(gbase) + (voff)[_i]), (LAS unsigned*)(lds + (bufoff) + ldsw + _i * 8192), 16, 0, 0); } while (0)
; #define PG8_LDA(dst, b, h) do { _Pragma("unroll") for (int m = 0; m < 4; ++m) _Pragma("unroll") for (int k = 0; k < 2; ++k) dst[m][k] = *(const LAS bf16x8*)(lds + PG8_SA(b, h) + aoff + m * 2048 + k * 1024); } while (0)
; #define PG8_LDB(dst, b, h) do { _Pragma("unroll") for (int n = 0; n < 2; ++n) _Pragma("unroll") for (int k = 0; k < 2; ++k) dst[n][k] = *(const LAS bf16x8*)(lds + PG8_SB(b, h) + boff + n * 2048 + k * 1024); } while (0)
; #define PG8_MMA(ai, bj, At, Bt) do { __builtin_amdgcn_s_setprio(3); _Pragma("unroll") for (int m = 0; m < 4; ++m) _Pragma("unroll") for (int n = 0; n < 2; ++n) _Pragma("unroll") for (int k = 0; k < 2; ++k) \
;         acc[ai][bj][m][n] = __builtin_amdgcn_mfma_f32_16x16x32_bf16(Bt[n][k], At[m][k], acc[ai][bj][m][n], 0, 0, 0); __builtin_amdgcn_s_setprio(0); } while (0)
; #define PG8_WAIT_V(n) asm volatile("s_waitcnt vmcnt(" #n ")" ::: "memory")
; #define PG8_WAIT_L(n) asm volatile("s_waitcnt lgkmcnt(" #n ")" ::: "memory")
; #define PG8_BAR __builtin_amdgcn_s_barrier()
; template <class Epi, class Sched, bool ALIGN_EPI = false, bool SP2 = false>
; __device__ __forceinline__ void gemm_phase(LAS unsigned char* lds, const Gemm g, const Sched& S, const Epi& E) {
;     ...
;             const char* a2 = last ? nA : cA + (size_t)(t + 2) * kstep; const char* b2 = last ? nB : cB + (size_t)(t + 2) * kstep;
;             const char* a3 = a2 + kstep; const char* b3 = b2 + kstep;
;             if (last && has_next) S.a_ready(nxt);
;             if constexpr (Epi::MID) { if (t == nt / 2) E.mid(acc, cur, wr, wc, fr, fq); }
;             if constexpr (SP2) {
;             PG8_LDB(B0, 0, 0); PG8_LDB(B1, 0, 1); PG8_SCHED; PG8_LDA(At, 0, 0); PG8_STAGE(PG8_SA(1, 1), a1 + hsA, voffA);
;             PG8_WAIT_V(8); PG8_WAIT_L(0); PG8_BAR; PG8_MMA(0, 0, At, B0); PG8_MMA(0, 1, At, B1); PG8_BAR; PG8_SCHED;
;             PG8_LDA(At, 0, 1); PG8_STAGE(PG8_SB(0, 0), b2, voffB); PG8_STAGE(PG8_SB(0, 1), b2 + hsB, voffB); PG8_STAGE(PG8_SA(0, 0), a2, voffA);
;             PG8_WAIT_V(8); PG8_WAIT_L(0); PG8_BAR; PG8_MMA(1, 0, At, B0); PG8_MMA(1, 1, At, B1); PG8_BAR; PG8_SCHED;
.LBB0_234:
	v_add_u32_e32 v1, s88, v194
	v_xor_b32_e32 v253, 64, v1
	ds_read_b128 v[84:87], v1
	ds_read_b128 v[96:99], v253
	ds_read_b128 v[140:143], v1 offset:2048
	ds_read_b128 v[144:147], v253 offset:2048
	v_add_u32_e32 v1, s89, v194
	v_xor_b32_e32 v253, 64, v1
	s_add_u32 s4, s64, s66
	ds_read_b128 v[152:155], v1
	ds_read_b128 v[156:159], v253
	ds_read_b128 v[160:163], v1 offset:2048
	ds_read_b128 v[182:185], v253 offset:2048
	s_addc_u32 s5, s65, s67
	s_add_u32 s4, s4, 0x100
	s_addc_u32 s5, s5, 0
	s_add_u32 s96, s93, s66
	s_addc_u32 s97, s94, s67
	s_cmpk_eq_i32 s66, 0x1f00
	s_cselect_b32 s9, s59, s5
	s_cselect_b32 s8, s91, s4
	s_cselect_b32 s5, s61, s97
	s_cselect_b32 s4, s60, s96
	s_sub_u32 s100, s66, 0x100000
	s_subb_u32 s101, s67, 0
	v_lshl_add_u64 v[242:243], v[148:149], 0, s[100:101]
	s_mov_b32 m0, s81
	v_lshl_add_u64 v[244:245], v[150:151], 0, s[100:101]
	global_load_lds_dwordx4 v[242:243], off
	s_mov_b32 m0, s82
	s_nop 0
	global_load_lds_dwordx4 v[244:245], off
	v_lshl_add_u64 v[2:3], v[148:149], 0, s[66:67]
	s_add_i32 m0, s41, 0xc000
	ds_read_b128 v[186:189], v198
	ds_read_b128 v[208:211], v250
	ds_read_b128 v[212:215], v198 offset:2048
	ds_read_b128 v[216:219], v250 offset:2048
	ds_read_b128 v[220:223], v198 offset:4096
	ds_read_b128 v[224:227], v250 offset:4096
	ds_read_b128 v[228:231], v198 offset:6144
	ds_read_b128 v[232:235], v250 offset:6144
	global_load_lds_dwordx4 v[2:3], off
	v_lshl_add_u64 v[2:3], v[150:151], 0, s[66:67]
	s_add_i32 m0, s41, 0xe000
	s_nop 0
	global_load_lds_dwordx4 v[2:3], off
	s_waitcnt vmcnt(8)
	s_waitcnt lgkmcnt(0)
	s_setprio 2
	s_barrier
	v_mfma_f32_16x16x32_bf16 v[136:139], v[84:87], v[186:189], v[136:139]
	v_mfma_f32_16x16x32_bf16 v[136:139], v[96:99], v[208:211], v[136:139]
	v_mfma_f32_16x16x32_bf16 v[132:135], v[140:143], v[186:189], v[132:135]
	v_mfma_f32_16x16x32_bf16 v[132:135], v[144:147], v[208:211], v[132:135]
	v_mfma_f32_16x16x32_bf16 v[120:123], v[84:87], v[212:215], v[120:123]
	v_mfma_f32_16x16x32_bf16 v[120:123], v[96:99], v[216:219], v[120:123]
	v_mfma_f32_16x16x32_bf16 v[116:119], v[140:143], v[212:215], v[116:119]
	v_mfma_f32_16x16x32_bf16 v[116:119], v[144:147], v[216:219], v[116:119]
	v_mfma_f32_16x16x32_bf16 v[104:107], v[84:87], v[220:223], v[104:107]
	v_mfma_f32_16x16x32_bf16 v[104:107], v[96:99], v[224:227], v[104:107]
	v_mfma_f32_16x16x32_bf16 v[100:103], v[140:143], v[220:223], v[100:103]
	v_mfma_f32_16x16x32_bf16 v[100:103], v[144:147], v[224:227], v[100:103]
	v_mfma_f32_16x16x32_bf16 v[80:83], v[84:87], v[228:231], v[80:83]
	v_mfma_f32_16x16x32_bf16 v[80:83], v[96:99], v[232:235], v[80:83]
	v_mfma_f32_16x16x32_bf16 v[76:79], v[140:143], v[228:231], v[76:79]
	v_mfma_f32_16x16x32_bf16 v[76:79], v[144:147], v[232:235], v[76:79]
	s_setprio 0
	s_setprio 2
	v_mfma_f32_16x16x32_bf16 v[128:131], v[152:155], v[186:189], v[128:131]
	v_mfma_f32_16x16x32_bf16 v[128:131], v[156:159], v[208:211], v[128:131]
	v_mfma_f32_16x16x32_bf16 v[124:127], v[160:163], v[186:189], v[124:127]
	v_mfma_f32_16x16x32_bf16 v[124:127], v[182:185], v[208:211], v[124:127]
	v_mfma_f32_16x16x32_bf16 v[112:115], v[152:155], v[212:215], v[112:115]
	v_mfma_f32_16x16x32_bf16 v[112:115], v[156:159], v[216:219], v[112:115]
	v_mfma_f32_16x16x32_bf16 v[108:111], v[160:163], v[212:215], v[108:111]
	v_mfma_f32_16x16x32_bf16 v[108:111], v[182:185], v[216:219], v[108:111]
	v_mfma_f32_16x16x32_bf16 v[92:95], v[152:155], v[220:223], v[92:95]
	v_mfma_f32_16x16x32_bf16 v[92:95], v[156:159], v[224:227], v[92:95]
	v_mfma_f32_16x16x32_bf16 v[88:91], v[160:163], v[220:223], v[88:91]
	v_mfma_f32_16x16x32_bf16 v[88:91], v[182:185], v[224:227], v[88:91]
	v_mfma_f32_16x16x32_bf16 v[72:75], v[152:155], v[228:231], v[72:75]
	v_mfma_f32_16x16x32_bf16 v[72:75], v[156:159], v[232:235], v[72:75]
	v_mfma_f32_16x16x32_bf16 v[68:71], v[160:163], v[228:231], v[68:71]
	s_setprio 3
	s_barrier
	v_mfma_f32_16x16x32_bf16 v[68:71], v[182:185], v[232:235], v[68:71]
	s_setprio 0
	s_add_i32 s96, s88, s31
	v_lshl_add_u64 v[190:191], s[4:5], 0, v[166:167]
	s_mov_b32 m0, s96
	ds_read_b128 v[186:189], v198 offset:16384
	ds_read_b128 v[208:211], v250 offset:16384
	ds_read_b128 v[212:215], v198 offset:18432
	ds_read_b128 v[216:219], v250 offset:18432
	ds_read_b128 v[220:223], v198 offset:20480
	ds_read_b128 v[224:227], v250 offset:20480
	ds_read_b128 v[228:231], v198 offset:22528
	ds_read_b128 v[232:235], v250 offset:22528
	global_load_lds_dwordx4 v[190:191], off
	s_add_i32 m0, s96, 0x2000
	s_add_u32 s96, s4, 0x104000
	v_lshl_add_u64 v[236:237], s[4:5], 0, v[170:171]
	s_addc_u32 s97, s5, 0
	s_add_i32 s98, s89, s31
	global_load_lds_dwordx4 v[236:237], off
	v_lshl_add_u64 v[2:3], s[96:97], 0, v[166:167]
	s_mov_b32 m0, s98
	s_nop 0
	global_load_lds_dwordx4 v[2:3], off
	v_lshl_add_u64 v[2:3], s[96:97], 0, v[170:171]
	s_add_i32 m0, s98, 0x2000
	s_nop 0
	global_load_lds_dwordx4 v[2:3], off
	s_waitcnt vmcnt(6)
	s_waitcnt lgkmcnt(0)
	s_setprio 2
	s_barrier
; #define PG8_STAGE(bufoff, gbase, voff) do { _Pragma("unroll") for (int _i = 0; _i < 2; ++_i) \
;         __builtin_amdgcn_global_load_lds((const unsigned*)((const char*)(gbase) + (voff)[_i]), (LAS unsigned*)(lds + (bufoff) + ldsw + _i * 8192), 16, 0, 0); } while (0)
; #define PG8_LDA(dst, b, h) do { _Pragma("unroll") for (int m = 0; m < 4; ++m) _Pragma("unroll") for (int k = 0; k < 2; ++k) dst[m][k] = *(const LAS bf16x8*)(lds + PG8_SA(b, h) + aoff + m * 2048 + k * 1024); } while (0)
; #define PG8_LDB(dst, b, h) do { _Pragma("unroll") for (int n = 0; n < 2; ++n) _Pragma("unroll") for (int k = 0; k < 2; ++k) dst[n][k] = *(const LAS bf16x8*)(lds + PG8_SB(b, h) + boff + n * 2048 + k * 1024); } while (0)
; #define PG8_MMA(ai, bj, At, Bt) do { __builtin_amdgcn_s_setprio(3); _Pragma("unroll") for (int m = 0; m < 4; ++m) _Pragma("unroll") for (int n = 0; n < 2; ++n) _Pragma("unroll") for (int k = 0; k < 2; ++k) \
;         acc[ai][bj][m][n] = __builtin_amdgcn_mfma_f32_16x16x32_bf16(Bt[n][k], At[m][k], acc[ai][bj][m][n], 0, 0, 0); __builtin_amdgcn_s_setprio(0); } while (0)
; #define PG8_WAIT_V(n) asm volatile("s_waitcnt vmcnt(" #n ")" ::: "memory")
; #define PG8_WAIT_L(n) asm volatile("s_waitcnt lgkmcnt(" #n ")" ::: "memory")
; #define PG8_BAR __builtin_amdgcn_s_barrier()
; #define PG8_SCHED __builtin_amdgcn_sched_barrier(0)
; template <class Epi, class Sched, bool ALIGN_EPI = false, bool SP2 = false>
; __device__ __forceinline__ void gemm_phase(LAS unsigned char* lds, const Gemm g, const Sched& S, const Epi& E) {
;     ...
;             PG8_WAIT_V(8); PG8_WAIT_L(0); PG8_BAR; PG8_MMA(1, 0, At, B0); PG8_MMA(1, 1, At, B1); PG8_BAR; PG8_SCHED;
;             PG8_LDB(B0, 1, 0); PG8_LDB(B1, 1, 1); PG8_SCHED; PG8_LDA(At, 1, 0); PG8_STAGE(PG8_SA(0, 1), a2 + hsA, voffA);
;             PG8_WAIT_V(8); PG8_WAIT_L(0); PG8_BAR; PG8_MMA(0, 0, At, B0); PG8_MMA(0, 1, At, B1); PG8_BAR; PG8_SCHED;
	v_mfma_f32_16x16x32_bf16 v[64:67], v[84:87], v[186:189], v[64:67]
	v_mfma_f32_16x16x32_bf16 v[64:67], v[96:99], v[208:211], v[64:67]
	v_mfma_f32_16x16x32_bf16 v[60:63], v[140:143], v[186:189], v[60:63]
	v_mfma_f32_16x16x32_bf16 v[60:63], v[144:147], v[208:211], v[60:63]
	v_mfma_f32_16x16x32_bf16 v[48:51], v[84:87], v[212:215], v[48:51]
	v_mfma_f32_16x16x32_bf16 v[48:51], v[96:99], v[216:219], v[48:51]
	v_mfma_f32_16x16x32_bf16 v[44:47], v[140:143], v[212:215], v[44:47]
	v_mfma_f32_16x16x32_bf16 v[44:47], v[144:147], v[216:219], v[44:47]
	v_mfma_f32_16x16x32_bf16 v[32:35], v[84:87], v[220:223], v[32:35]
	v_mfma_f32_16x16x32_bf16 v[32:35], v[96:99], v[224:227], v[32:35]
	v_mfma_f32_16x16x32_bf16 v[28:31], v[140:143], v[220:223], v[28:31]
	v_mfma_f32_16x16x32_bf16 v[28:31], v[144:147], v[224:227], v[28:31]
	v_mfma_f32_16x16x32_bf16 v[16:19], v[84:87], v[228:231], v[16:19]
	v_mfma_f32_16x16x32_bf16 v[16:19], v[96:99], v[232:235], v[16:19]
	v_mfma_f32_16x16x32_bf16 v[12:15], v[140:143], v[228:231], v[12:15]
	v_mfma_f32_16x16x32_bf16 v[12:15], v[144:147], v[232:235], v[12:15]
	s_setprio 0
	s_setprio 2
	v_mfma_f32_16x16x32_bf16 v[56:59], v[152:155], v[186:189], v[56:59]
	v_mfma_f32_16x16x32_bf16 v[56:59], v[156:159], v[208:211], v[56:59]
	v_mfma_f32_16x16x32_bf16 v[52:55], v[160:163], v[186:189], v[52:55]
	v_mfma_f32_16x16x32_bf16 v[52:55], v[182:185], v[208:211], v[52:55]
	v_mfma_f32_16x16x32_bf16 v[40:43], v[152:155], v[212:215], v[40:43]
	v_mfma_f32_16x16x32_bf16 v[40:43], v[156:159], v[216:219], v[40:43]
	v_mfma_f32_16x16x32_bf16 v[36:39], v[160:163], v[212:215], v[36:39]
	v_mfma_f32_16x16x32_bf16 v[36:39], v[182:185], v[216:219], v[36:39]
	v_mfma_f32_16x16x32_bf16 v[24:27], v[152:155], v[220:223], v[24:27]
	v_mfma_f32_16x16x32_bf16 v[24:27], v[156:159], v[224:227], v[24:27]
	v_mfma_f32_16x16x32_bf16 v[20:23], v[160:163], v[220:223], v[20:23]
	v_mfma_f32_16x16x32_bf16 v[20:23], v[182:185], v[224:227], v[20:23]
	v_mfma_f32_16x16x32_bf16 v[8:11], v[152:155], v[228:231], v[8:11]
	v_mfma_f32_16x16x32_bf16 v[8:11], v[156:159], v[232:235], v[8:11]
	v_mfma_f32_16x16x32_bf16 v[2:5], v[160:163], v[228:231], v[4:7]
	s_setprio 3
	s_barrier
	v_mfma_f32_16x16x32_bf16 v[2:5], v[182:185], v[232:235], v[2:5]
	s_setprio 0
	s_add_i32 s96, 0, 0x18000
	v_add_u32_e32 v1, s96, v194
	v_xor_b32_e32 v253, 64, v1
	s_add_i32 s97, 0, 0x1c000
	ds_read_b128 v[84:87], v1
	ds_read_b128 v[96:99], v253
	ds_read_b128 v[140:143], v1 offset:2048
	ds_read_b128 v[144:147], v253 offset:2048
	v_add_u32_e32 v1, s97, v194
	v_xor_b32_e32 v253, 64, v1
	ds_read_b128 v[152:155], v1
	ds_read_b128 v[156:159], v253
	ds_read_b128 v[160:163], v1 offset:2048
	ds_read_b128 v[182:185], v253 offset:2048
	v_lshl_add_u64 v[242:243], s[8:9], 0, v[164:165]
	s_mov_b32 m0, s41
	v_lshl_add_u64 v[244:245], s[8:9], 0, v[168:169]
	global_load_lds_dwordx4 v[242:243], off
	s_mov_b32 m0, s68
	s_nop 0
	global_load_lds_dwordx4 v[244:245], off
	s_add_u32 s8, s8, 0x100000
	s_addc_u32 s9, s9, 0
	s_mov_b32 m0, s69
	v_lshl_add_u64 v[6:7], s[8:9], 0, v[164:165]
	ds_read_b128 v[186:189], v198 offset:32768
	ds_read_b128 v[208:211], v250 offset:32768
	ds_read_b128 v[212:215], v198 offset:34816
	ds_read_b128 v[216:219], v250 offset:34816
	ds_read_b128 v[220:223], v198 offset:36864
	ds_read_b128 v[224:227], v250 offset:36864
	ds_read_b128 v[228:231], v198 offset:38912
	ds_read_b128 v[232:235], v250 offset:38912
	global_load_lds_dwordx4 v[6:7], off
	v_lshl_add_u64 v[6:7], s[8:9], 0, v[168:169]
	s_mov_b32 m0, s70
	s_nop 0
	global_load_lds_dwordx4 v[6:7], off
	s_waitcnt vmcnt(8)
	s_waitcnt lgkmcnt(0)
	s_setprio 2
	s_barrier
; #define PG8_STAGE(bufoff, gbase, voff) do { _Pragma("unroll") for (int _i = 0; _i < 2; ++_i) \
;         __builtin_amdgcn_global_load_lds((const unsigned*)((const char*)(gbase) + (voff)[_i]), (LAS unsigned*)(lds + (bufoff) + ldsw + _i * 8192), 16, 0, 0); } while (0)
; #define PG8_LDA(dst, b, h) do { _Pragma("unroll") for (int m = 0; m < 4; ++m) _Pragma("unroll") for (int k = 0; k < 2; ++k) dst[m][k] = *(const LAS bf16x8*)(lds + PG8_SA(b, h) + aoff + m * 2048 + k * 1024); } while (0)
; #define PG8_MMA(ai, bj, At, Bt) do { __builtin_amdgcn_s_setprio(3); _Pragma("unroll") for (int m = 0; m < 4; ++m) _Pragma("unroll") for (int n = 0; n < 2; ++n) _Pragma("unroll") for (int k = 0; k < 2; ++k) \
;         acc[ai][bj][m][n] = __builtin_amdgcn_mfma_f32_16x16x32_bf16(Bt[n][k], At[m][k], acc[ai][bj][m][n], 0, 0, 0); __builtin_amdgcn_s_setprio(0); } while (0)
; #define PG8_WAIT_V(n) asm volatile("s_waitcnt vmcnt(" #n ")" ::: "memory")
; #define PG8_WAIT_L(n) asm volatile("s_waitcnt lgkmcnt(" #n ")" ::: "memory")
; #define PG8_BAR __builtin_amdgcn_s_barrier()
; #define PG8_SCHED __builtin_amdgcn_sched_barrier(0)
; template <class Epi, class Sched, bool ALIGN_EPI = false, bool SP2 = false>
; __device__ __forceinline__ void gemm_phase(LAS unsigned char* lds, const Gemm g, const Sched& S, const Epi& E) {
;     ...
;             PG8_WAIT_V(8); PG8_WAIT_L(0); PG8_BAR; PG8_MMA(0, 0, At, B0); PG8_MMA(0, 1, At, B1); PG8_BAR; PG8_SCHED;
;             PG8_LDA(At, 1, 1); PG8_STAGE(PG8_SB(1, 0), b3, voffB); PG8_STAGE(PG8_SB(1, 1), b3 + hsB, voffB); PG8_STAGE(PG8_SA(1, 0), a3, voffA);
;             PG8_WAIT_V(8); PG8_WAIT_L(0); PG8_BAR; PG8_MMA(1, 0, At, B0); PG8_MMA(1, 1, At, B1); PG8_BAR; PG8_SCHED;
	v_mfma_f32_16x16x32_bf16 v[136:139], v[84:87], v[186:189], v[136:139]
	v_mfma_f32_16x16x32_bf16 v[136:139], v[96:99], v[208:211], v[136:139]
	v_mfma_f32_16x16x32_bf16 v[132:135], v[140:143], v[186:189], v[132:135]
	v_mfma_f32_16x16x32_bf16 v[132:135], v[144:147], v[208:211], v[132:135]
	v_mfma_f32_16x16x32_bf16 v[120:123], v[84:87], v[212:215], v[120:123]
	v_mfma_f32_16x16x32_bf16 v[120:123], v[96:99], v[216:219], v[120:123]
	v_mfma_f32_16x16x32_bf16 v[116:119], v[140:143], v[212:215], v[116:119]
	v_mfma_f32_16x16x32_bf16 v[116:119], v[144:147], v[216:219], v[116:119]
	v_mfma_f32_16x16x32_bf16 v[104:107], v[84:87], v[220:223], v[104:107]
	v_mfma_f32_16x16x32_bf16 v[104:107], v[96:99], v[224:227], v[104:107]
	v_mfma_f32_16x16x32_bf16 v[100:103], v[140:143], v[220:223], v[100:103]
	v_mfma_f32_16x16x32_bf16 v[100:103], v[144:147], v[224:227], v[100:103]
	v_mfma_f32_16x16x32_bf16 v[80:83], v[84:87], v[228:231], v[80:83]
	v_mfma_f32_16x16x32_bf16 v[80:83], v[96:99], v[232:235], v[80:83]
	v_mfma_f32_16x16x32_bf16 v[76:79], v[140:143], v[228:231], v[76:79]
	v_mfma_f32_16x16x32_bf16 v[76:79], v[144:147], v[232:235], v[76:79]
	s_setprio 0
	s_setprio 2
	v_mfma_f32_16x16x32_bf16 v[128:131], v[152:155], v[186:189], v[128:131]
	v_mfma_f32_16x16x32_bf16 v[128:131], v[156:159], v[208:211], v[128:131]
	v_mfma_f32_16x16x32_bf16 v[124:127], v[160:163], v[186:189], v[124:127]
	v_mfma_f32_16x16x32_bf16 v[124:127], v[182:185], v[208:211], v[124:127]
	v_mfma_f32_16x16x32_bf16 v[112:115], v[152:155], v[212:215], v[112:115]
	v_mfma_f32_16x16x32_bf16 v[112:115], v[156:159], v[216:219], v[112:115]
	v_mfma_f32_16x16x32_bf16 v[108:111], v[160:163], v[212:215], v[108:111]
	v_mfma_f32_16x16x32_bf16 v[108:111], v[182:185], v[216:219], v[108:111]
	v_mfma_f32_16x16x32_bf16 v[92:95], v[152:155], v[220:223], v[92:95]
	v_mfma_f32_16x16x32_bf16 v[92:95], v[156:159], v[224:227], v[92:95]
	v_mfma_f32_16x16x32_bf16 v[88:91], v[160:163], v[220:223], v[88:91]
	v_mfma_f32_16x16x32_bf16 v[88:91], v[182:185], v[224:227], v[88:91]
	v_mfma_f32_16x16x32_bf16 v[72:75], v[152:155], v[228:231], v[72:75]
	v_mfma_f32_16x16x32_bf16 v[72:75], v[156:159], v[232:235], v[72:75]
	v_mfma_f32_16x16x32_bf16 v[68:71], v[160:163], v[228:231], v[68:71]
	s_setprio 3
	s_barrier
	v_mfma_f32_16x16x32_bf16 v[68:71], v[182:185], v[232:235], v[68:71]
	s_setprio 0
	s_add_i32 s8, s96, s31
	v_lshl_add_u64 v[6:7], v[190:191], 0, s[24:25]
	s_mov_b32 m0, s8
	ds_read_b128 v[186:189], v198 offset:49152
	ds_read_b128 v[208:211], v250 offset:49152
	ds_read_b128 v[212:215], v198 offset:51200
	ds_read_b128 v[216:219], v250 offset:51200
	ds_read_b128 v[220:223], v198 offset:53248
	ds_read_b128 v[224:227], v250 offset:53248
	ds_read_b128 v[228:231], v198 offset:55296
	ds_read_b128 v[232:235], v250 offset:55296
	global_load_lds_dwordx4 v[6:7], off
	s_add_i32 m0, s8, 0x2000
	s_add_u32 s4, s4, 0x104080
	v_lshl_add_u64 v[6:7], v[236:237], 0, s[24:25]
	s_addc_u32 s5, s5, 0
	s_add_i32 s8, s97, s31
	global_load_lds_dwordx4 v[6:7], off
	v_lshl_add_u64 v[6:7], s[4:5], 0, v[166:167]
	s_mov_b32 m0, s8
	s_nop 0
	global_load_lds_dwordx4 v[6:7], off
	v_lshl_add_u64 v[6:7], s[4:5], 0, v[170:171]
	s_add_i32 m0, s8, 0x2000
	s_nop 0
	global_load_lds_dwordx4 v[6:7], off
	s_waitcnt vmcnt(6)
	s_waitcnt lgkmcnt(0)
	s_setprio 2
	s_barrier
	v_mfma_f32_16x16x32_bf16 v[64:67], v[84:87], v[186:189], v[64:67]
	v_mfma_f32_16x16x32_bf16 v[64:67], v[96:99], v[208:211], v[64:67]
	v_mfma_f32_16x16x32_bf16 v[60:63], v[140:143], v[186:189], v[60:63]
	v_mfma_f32_16x16x32_bf16 v[60:63], v[144:147], v[208:211], v[60:63]
	v_mfma_f32_16x16x32_bf16 v[48:51], v[84:87], v[212:215], v[48:51]
	v_mfma_f32_16x16x32_bf16 v[48:51], v[96:99], v[216:219], v[48:51]
	v_mfma_f32_16x16x32_bf16 v[44:47], v[140:143], v[212:215], v[44:47]
	v_mfma_f32_16x16x32_bf16 v[44:47], v[144:147], v[216:219], v[44:47]
	v_mfma_f32_16x16x32_bf16 v[32:35], v[84:87], v[220:223], v[32:35]
	v_mfma_f32_16x16x32_bf16 v[32:35], v[96:99], v[224:227], v[32:35]
	v_mfma_f32_16x16x32_bf16 v[28:31], v[140:143], v[220:223], v[28:31]
	v_mfma_f32_16x16x32_bf16 v[28:31], v[144:147], v[224:227], v[28:31]
	v_mfma_f32_16x16x32_bf16 v[16:19], v[84:87], v[228:231], v[16:19]
	v_mfma_f32_16x16x32_bf16 v[16:19], v[96:99], v[232:235], v[16:19]
	v_mfma_f32_16x16x32_bf16 v[12:15], v[140:143], v[228:231], v[12:15]
	v_mfma_f32_16x16x32_bf16 v[12:15], v[144:147], v[232:235], v[12:15]
	s_setprio 0
	s_setprio 2
	v_mfma_f32_16x16x32_bf16 v[56:59], v[152:155], v[186:189], v[56:59]
	v_mfma_f32_16x16x32_bf16 v[56:59], v[156:159], v[208:211], v[56:59]
	v_mfma_f32_16x16x32_bf16 v[52:55], v[160:163], v[186:189], v[52:55]
	v_mfma_f32_16x16x32_bf16 v[52:55], v[182:185], v[208:211], v[52:55]
	v_mfma_f32_16x16x32_bf16 v[40:43], v[152:155], v[212:215], v[40:43]
	v_mfma_f32_16x16x32_bf16 v[40:43], v[156:159], v[216:219], v[40:43]
	v_mfma_f32_16x16x32_bf16 v[36:39], v[160:163], v[212:215], v[36:39]
	v_mfma_f32_16x16x32_bf16 v[36:39], v[182:185], v[216:219], v[36:39]
	v_mfma_f32_16x16x32_bf16 v[24:27], v[152:155], v[220:223], v[24:27]
	v_mfma_f32_16x16x32_bf16 v[24:27], v[156:159], v[224:227], v[24:27]
	v_mfma_f32_16x16x32_bf16 v[20:23], v[160:163], v[220:223], v[20:23]
	v_mfma_f32_16x16x32_bf16 v[20:23], v[182:185], v[224:227], v[20:23]
	v_mfma_f32_16x16x32_bf16 v[6:9], v[152:155], v[228:231], v[8:11]
	v_mfma_f32_16x16x32_bf16 v[8:11], v[156:159], v[232:235], v[6:9]
	v_mfma_f32_16x16x32_bf16 v[2:5], v[160:163], v[228:231], v[2:5]
	s_setprio 3
	s_barrier
	v_mfma_f32_16x16x32_bf16 v[4:7], v[182:185], v[232:235], v[2:5]
	s_setprio 0
	s_add_i32 s95, s95, 2
	s_add_u32 s66, s66, 0x100
	s_addc_u32 s67, s67, 0
	s_cmp_gt_u32 s95, 61
	s_cbranch_scc1 .LBB0_237

; #define PG8_STAGE(bufoff, gbase, voff) do { _Pragma("unroll") for (int _i = 0; _i < 2; ++_i) \
;         __builtin_amdgcn_global_load_lds((const unsigned*)((const char*)(gbase) + (voff)[_i]), (LAS unsigned*)(lds + (bufoff) + ldsw + _i * 8192), 16, 0, 0); } while (0)
; #define PG8_LDA(dst, b, h) do { _Pragma("unroll") for (int m = 0; m < 4; ++m) _Pragma("unroll") for (int k = 0; k < 2; ++k) dst[m][k] = *(const LAS bf16x8*)(lds + PG8_SA(b, h) + aoff + m * 2048 + k * 1024); } while (0)
; #define PG8_LDB(dst, b, h) do { _Pragma("unroll") for (int n = 0; n < 2; ++n) _Pragma("unroll") for (int k = 0; k < 2; ++k) dst[n][k] = *(const LAS bf16x8*)(lds + PG8_SB(b, h) + boff + n * 2048 + k * 1024); } while (0)
; #define PG8_MMA(ai, bj, At, Bt) do { __builtin_amdgcn_s_setprio(3); _Pragma("unroll") for (int m = 0; m < 4; ++m) _Pragma("unroll") for (int n = 0; n < 2; ++n) _Pragma("unroll") for (int k = 0; k < 2; ++k) \
;         acc[ai][bj][m][n] = __builtin_amdgcn_mfma_f32_16x16x32_bf16(Bt[n][k], At[m][k], acc[ai][bj][m][n], 0, 0, 0); __builtin_amdgcn_s_setprio(0); } while (0)
; #define PG8_WAIT_V(n) asm volatile("s_waitcnt vmcnt(" #n ")" ::: "memory")
; #define PG8_WAIT_L(n) asm volatile("s_waitcnt lgkmcnt(" #n ")" ::: "memory")
; #define PG8_BAR __builtin_amdgcn_s_barrier()
; template <class Epi, class Sched, bool ALIGN_EPI = false, bool SP2 = false>
; __device__ __forceinline__ void gemm_phase(LAS unsigned char* lds, const Gemm g, const Sched& S, const Epi& E) {
;     ...
;             const bool last = (t == nt - 2);
;             const char* a1 = cA + (size_t)(t + 1) * kstep;
;             const char* a2 = last ? nA : cA + (size_t)(t + 2) * kstep; const char* b2 = last ? nB : cB + (size_t)(t + 2) * kstep;
;             const char* a3 = a2 + kstep; const char* b3 = b2 + kstep;
;             if (last && has_next) S.a_ready(nxt);
;             if constexpr (Epi::MID) { if (t == nt / 2) E.mid(acc, cur, wr, wc, fr, fq); }
;             if constexpr (SP2) {
;             PG8_LDB(B0, 0, 0); PG8_LDB(B1, 0, 1); PG8_SCHED; PG8_LDA(At, 0, 0); PG8_STAGE(PG8_SA(1, 1), a1 + hsA, voffA);
;             PG8_WAIT_V(8); PG8_WAIT_L(0); PG8_BAR; PG8_MMA(0, 0, At, B0); PG8_MMA(0, 1, At, B1); PG8_BAR; PG8_SCHED;
;             PG8_LDA(At, 0, 1); PG8_STAGE(PG8_SB(0, 0), b2, voffB); PG8_STAGE(PG8_SB(0, 1), b2 + hsB, voffB); PG8_STAGE(PG8_SA(0, 0), a2, voffA);
.LBB0_309:
	ds_read_b128 v[112:115], v175
	ds_read_b128 v[132:135], v251
	ds_read_b128 v[136:139], v175 offset:2048
	ds_read_b128 v[140:143], v251 offset:2048
	ds_read_b128 v[144:147], v176
	ds_read_b128 v[148:151], v252
	ds_read_b128 v[184:187], v176 offset:2048
	ds_read_b128 v[188:191], v252 offset:2048
	s_add_u32 s24, s4, 0xffefc080
	s_addc_u32 s25, s5, -1
	s_cmp_eq_u32 s73, 60
	s_cselect_b32 s27, s11, s25
	s_cselect_b32 s26, s10, s24
	s_cselect_b32 s25, s21, s72
	s_cselect_b32 s24, s20, s71
	s_sub_u32 s100, s4, 0x104000
	s_subb_u32 s101, s5, 0
	v_lshl_add_u64 v[242:243], s[100:101], 0, v[152:153]
	s_mov_b32 m0, s42
	v_lshl_add_u64 v[244:245], s[100:101], 0, v[156:157]
	global_load_lds_dwordx4 v[242:243], off
	s_mov_b32 m0, s43
	s_nop 0
	global_load_lds_dwordx4 v[244:245], off
	v_lshl_add_u64 v[200:201], s[4:5], 0, v[164:165]
	s_add_i32 m0, s36, 0xc000
	ds_read_b128 v[192:195], v177
	ds_read_b128 v[196:199], v250
	ds_read_b128 v[206:209], v177 offset:2048
	ds_read_b128 v[210:213], v250 offset:2048
	ds_read_b128 v[214:217], v177 offset:4096
	ds_read_b128 v[218:221], v250 offset:4096
	ds_read_b128 v[222:225], v177 offset:6144
	ds_read_b128 v[226:229], v250 offset:6144
	global_load_lds_dwordx4 v[200:201], off
	v_lshl_add_u64 v[200:201], s[4:5], 0, v[166:167]
	s_add_i32 m0, s36, 0xe000
	s_nop 0
	global_load_lds_dwordx4 v[200:201], off
	s_waitcnt vmcnt(8)
	s_waitcnt lgkmcnt(0)
	s_setprio 2
	s_barrier
	v_mfma_f32_16x16x32_bf16 v[128:131], v[112:115], v[192:195], v[128:131]
	v_mfma_f32_16x16x32_bf16 v[128:131], v[132:135], v[196:199], v[128:131]
	v_mfma_f32_16x16x32_bf16 v[124:127], v[136:139], v[192:195], v[124:127]
	v_mfma_f32_16x16x32_bf16 v[124:127], v[140:143], v[196:199], v[124:127]
	v_mfma_f32_16x16x32_bf16 v[108:111], v[112:115], v[206:209], v[108:111]
	v_mfma_f32_16x16x32_bf16 v[108:111], v[132:135], v[210:213], v[108:111]
	v_mfma_f32_16x16x32_bf16 v[104:107], v[136:139], v[206:209], v[104:107]
	v_mfma_f32_16x16x32_bf16 v[104:107], v[140:143], v[210:213], v[104:107]
	v_mfma_f32_16x16x32_bf16 v[92:95], v[112:115], v[214:217], v[92:95]
	v_mfma_f32_16x16x32_bf16 v[92:95], v[132:135], v[218:221], v[92:95]
	v_mfma_f32_16x16x32_bf16 v[88:91], v[136:139], v[214:217], v[88:91]
	v_mfma_f32_16x16x32_bf16 v[88:91], v[140:143], v[218:221], v[88:91]
	v_mfma_f32_16x16x32_bf16 v[76:79], v[112:115], v[222:225], v[76:79]
	v_mfma_f32_16x16x32_bf16 v[76:79], v[132:135], v[226:229], v[76:79]
	v_mfma_f32_16x16x32_bf16 v[72:75], v[136:139], v[222:225], v[72:75]
	v_mfma_f32_16x16x32_bf16 v[72:75], v[140:143], v[226:229], v[72:75]
	s_setprio 0
	s_setprio 2
	v_mfma_f32_16x16x32_bf16 v[120:123], v[144:147], v[192:195], v[120:123]
	v_mfma_f32_16x16x32_bf16 v[120:123], v[148:151], v[196:199], v[120:123]
	v_mfma_f32_16x16x32_bf16 v[116:119], v[184:187], v[192:195], v[116:119]
	v_mfma_f32_16x16x32_bf16 v[116:119], v[188:191], v[196:199], v[116:119]
	v_mfma_f32_16x16x32_bf16 v[100:103], v[144:147], v[206:209], v[100:103]
	v_mfma_f32_16x16x32_bf16 v[100:103], v[148:151], v[210:213], v[100:103]
	v_mfma_f32_16x16x32_bf16 v[96:99], v[184:187], v[206:209], v[96:99]
	v_mfma_f32_16x16x32_bf16 v[96:99], v[188:191], v[210:213], v[96:99]
	v_mfma_f32_16x16x32_bf16 v[84:87], v[144:147], v[214:217], v[84:87]
	v_mfma_f32_16x16x32_bf16 v[84:87], v[148:151], v[218:221], v[84:87]
	v_mfma_f32_16x16x32_bf16 v[80:83], v[184:187], v[214:217], v[80:83]
	v_mfma_f32_16x16x32_bf16 v[80:83], v[188:191], v[218:221], v[80:83]
	v_mfma_f32_16x16x32_bf16 v[68:71], v[144:147], v[222:225], v[68:71]
	v_mfma_f32_16x16x32_bf16 v[68:71], v[148:151], v[226:229], v[68:71]
	v_mfma_f32_16x16x32_bf16 v[64:67], v[184:187], v[222:225], v[64:67]
	s_setprio 3
	s_barrier
	v_mfma_f32_16x16x32_bf16 v[64:67], v[188:191], v[226:229], v[64:67]
	s_setprio 0
	s_add_i32 s74, s45, s31
	v_lshl_add_u64 v[200:201], s[24:25], 0, v[154:155]
	s_mov_b32 m0, s74
	ds_read_b128 v[192:195], v177 offset:16384
	ds_read_b128 v[196:199], v250 offset:16384
	ds_read_b128 v[206:209], v177 offset:18432
	ds_read_b128 v[210:213], v250 offset:18432
	ds_read_b128 v[214:217], v177 offset:20480
	ds_read_b128 v[218:221], v250 offset:20480
	ds_read_b128 v[222:225], v177 offset:22528
	ds_read_b128 v[226:229], v250 offset:22528
	global_load_lds_dwordx4 v[200:201], off
	s_add_i32 m0, s74, 0x2000
	s_add_u32 s74, s24, 0x41000
	v_lshl_add_u64 v[230:231], s[24:25], 0, v[158:159]
	s_addc_u32 s75, s25, 0
	s_add_i32 s78, s46, s31
	global_load_lds_dwordx4 v[230:231], off
	v_lshl_add_u64 v[232:233], s[74:75], 0, v[154:155]
	s_mov_b32 m0, s78
	s_nop 0
	global_load_lds_dwordx4 v[232:233], off
	v_lshl_add_u64 v[232:233], s[74:75], 0, v[158:159]
	s_add_i32 m0, s78, 0x2000
	s_nop 0
	global_load_lds_dwordx4 v[232:233], off
	s_waitcnt vmcnt(6)
	s_waitcnt lgkmcnt(0)
	s_setprio 2
	s_barrier
; #define PG8_STAGE(bufoff, gbase, voff) do { _Pragma("unroll") for (int _i = 0; _i < 2; ++_i) \
;         __builtin_amdgcn_global_load_lds((const unsigned*)((const char*)(gbase) + (voff)[_i]), (LAS unsigned*)(lds + (bufoff) + ldsw + _i * 8192), 16, 0, 0); } while (0)
; #define PG8_LDA(dst, b, h) do { _Pragma("unroll") for (int m = 0; m < 4; ++m) _Pragma("unroll") for (int k = 0; k < 2; ++k) dst[m][k] = *(const LAS bf16x8*)(lds + PG8_SA(b, h) + aoff + m * 2048 + k * 1024); } while (0)
; #define PG8_LDB(dst, b, h) do { _Pragma("unroll") for (int n = 0; n < 2; ++n) _Pragma("unroll") for (int k = 0; k < 2; ++k) dst[n][k] = *(const LAS bf16x8*)(lds + PG8_SB(b, h) + boff + n * 2048 + k * 1024); } while (0)
; #define PG8_MMA(ai, bj, At, Bt) do { __builtin_amdgcn_s_setprio(3); _Pragma("unroll") for (int m = 0; m < 4; ++m) _Pragma("unroll") for (int n = 0; n < 2; ++n) _Pragma("unroll") for (int k = 0; k < 2; ++k) \
;         acc[ai][bj][m][n] = __builtin_amdgcn_mfma_f32_16x16x32_bf16(Bt[n][k], At[m][k], acc[ai][bj][m][n], 0, 0, 0); __builtin_amdgcn_s_setprio(0); } while (0)
; #define PG8_WAIT_V(n) asm volatile("s_waitcnt vmcnt(" #n ")" ::: "memory")
; #define PG8_WAIT_L(n) asm volatile("s_waitcnt lgkmcnt(" #n ")" ::: "memory")
; #define PG8_BAR __builtin_amdgcn_s_barrier()
; #define PG8_SCHED __builtin_amdgcn_sched_barrier(0)
; template <class Epi, class Sched, bool ALIGN_EPI = false, bool SP2 = false>
; __device__ __forceinline__ void gemm_phase(LAS unsigned char* lds, const Gemm g, const Sched& S, const Epi& E) {
;     ...
;             PG8_WAIT_V(8); PG8_WAIT_L(0); PG8_BAR; PG8_MMA(1, 0, At, B0); PG8_MMA(1, 1, At, B1); PG8_BAR; PG8_SCHED;
;             PG8_LDB(B0, 1, 0); PG8_LDB(B1, 1, 1); PG8_SCHED; PG8_LDA(At, 1, 0); PG8_STAGE(PG8_SA(0, 1), a2 + hsA, voffA);
	v_mfma_f32_16x16x32_bf16 v[60:63], v[112:115], v[192:195], v[60:63]
	v_mfma_f32_16x16x32_bf16 v[60:63], v[132:135], v[196:199], v[60:63]
	v_mfma_f32_16x16x32_bf16 v[56:59], v[136:139], v[192:195], v[56:59]
	v_mfma_f32_16x16x32_bf16 v[56:59], v[140:143], v[196:199], v[56:59]
	v_mfma_f32_16x16x32_bf16 v[44:47], v[112:115], v[206:209], v[44:47]
	v_mfma_f32_16x16x32_bf16 v[44:47], v[132:135], v[210:213], v[44:47]
	v_mfma_f32_16x16x32_bf16 v[40:43], v[136:139], v[206:209], v[40:43]
	v_mfma_f32_16x16x32_bf16 v[40:43], v[140:143], v[210:213], v[40:43]
	v_mfma_f32_16x16x32_bf16 v[28:31], v[112:115], v[214:217], v[28:31]
	v_mfma_f32_16x16x32_bf16 v[28:31], v[132:135], v[218:221], v[28:31]
	v_mfma_f32_16x16x32_bf16 v[24:27], v[136:139], v[214:217], v[24:27]
	v_mfma_f32_16x16x32_bf16 v[24:27], v[140:143], v[218:221], v[24:27]
	v_mfma_f32_16x16x32_bf16 v[12:15], v[112:115], v[222:225], v[12:15]
	v_mfma_f32_16x16x32_bf16 v[12:15], v[132:135], v[226:229], v[12:15]
	v_mfma_f32_16x16x32_bf16 v[8:11], v[136:139], v[222:225], v[8:11]
	v_mfma_f32_16x16x32_bf16 v[8:11], v[140:143], v[226:229], v[8:11]
	s_setprio 0
	s_setprio 2
	v_mfma_f32_16x16x32_bf16 v[52:55], v[144:147], v[192:195], v[52:55]
	v_mfma_f32_16x16x32_bf16 v[52:55], v[148:151], v[196:199], v[52:55]
	v_mfma_f32_16x16x32_bf16 v[48:51], v[184:187], v[192:195], v[48:51]
	v_mfma_f32_16x16x32_bf16 v[48:51], v[188:191], v[196:199], v[48:51]
	v_mfma_f32_16x16x32_bf16 v[36:39], v[144:147], v[206:209], v[36:39]
	v_mfma_f32_16x16x32_bf16 v[36:39], v[148:151], v[210:213], v[36:39]
	v_mfma_f32_16x16x32_bf16 v[32:35], v[184:187], v[206:209], v[32:35]
	v_mfma_f32_16x16x32_bf16 v[32:35], v[188:191], v[210:213], v[32:35]
	v_mfma_f32_16x16x32_bf16 v[20:23], v[144:147], v[214:217], v[20:23]
	v_mfma_f32_16x16x32_bf16 v[20:23], v[148:151], v[218:221], v[20:23]
	v_mfma_f32_16x16x32_bf16 v[16:19], v[184:187], v[214:217], v[16:19]
	v_mfma_f32_16x16x32_bf16 v[16:19], v[188:191], v[218:221], v[16:19]
	v_mfma_f32_16x16x32_bf16 v[4:7], v[144:147], v[222:225], v[4:7]
	v_mfma_f32_16x16x32_bf16 v[4:7], v[148:151], v[226:229], v[4:7]
	v_mfma_f32_16x16x32_bf16 v[0:3], v[184:187], v[222:225], v[0:3]
	s_setprio 3
	s_barrier
	v_mfma_f32_16x16x32_bf16 v[0:3], v[188:191], v[226:229], v[0:3]
	s_setprio 0
	s_add_i32 s74, 0, 0x18000
	s_add_i32 s75, 0, 0x1c000
	v_add_u32_e32 v140, s74, v173
	v_xor_b32_e32 v253, 64, v140
	v_add_u32_e32 v188, s75, v173
	v_xor_b32_e32 v254, 64, v188
	ds_read_b128 v[112:115], v140
	ds_read_b128 v[132:135], v253
	ds_read_b128 v[136:139], v140 offset:2048
	ds_read_b128 v[140:143], v253 offset:2048
	ds_read_b128 v[144:147], v188
	ds_read_b128 v[148:151], v254
	ds_read_b128 v[184:187], v188 offset:2048
	ds_read_b128 v[188:191], v254 offset:2048
	v_lshl_add_u64 v[242:243], s[26:27], 0, v[152:153]
	s_mov_b32 m0, s36
	v_lshl_add_u64 v[244:245], s[26:27], 0, v[156:157]
	global_load_lds_dwordx4 v[242:243], off
	s_mov_b32 m0, s37
	s_nop 0
	global_load_lds_dwordx4 v[244:245], off
	s_add_u32 s26, s26, 0x104000
	s_addc_u32 s27, s27, 0
	s_mov_b32 m0, s38
	v_lshl_add_u64 v[236:237], s[26:27], 0, v[152:153]
	ds_read_b128 v[192:195], v177 offset:32768
	ds_read_b128 v[196:199], v250 offset:32768
	ds_read_b128 v[206:209], v177 offset:34816
	ds_read_b128 v[210:213], v250 offset:34816
	ds_read_b128 v[214:217], v177 offset:36864
	ds_read_b128 v[218:221], v250 offset:36864
	ds_read_b128 v[222:225], v177 offset:38912
	ds_read_b128 v[226:229], v250 offset:38912
	global_load_lds_dwordx4 v[236:237], off
	v_lshl_add_u64 v[236:237], s[26:27], 0, v[156:157]
	s_mov_b32 m0, s39
	s_nop 0
	global_load_lds_dwordx4 v[236:237], off
	s_waitcnt vmcnt(8)
	s_waitcnt lgkmcnt(0)
	s_setprio 2
	s_barrier
; #define PG8_STAGE(bufoff, gbase, voff) do { _Pragma("unroll") for (int _i = 0; _i < 2; ++_i) \
;         __builtin_amdgcn_global_load_lds((const unsigned*)((const char*)(gbase) + (voff)[_i]), (LAS unsigned*)(lds + (bufoff) + ldsw + _i * 8192), 16, 0, 0); } while (0)
; #define PG8_LDA(dst, b, h) do { _Pragma("unroll") for (int m = 0; m < 4; ++m) _Pragma("unroll") for (int k = 0; k < 2; ++k) dst[m][k] = *(const LAS bf16x8*)(lds + PG8_SA(b, h) + aoff + m * 2048 + k * 1024); } while (0)
; #define PG8_MMA(ai, bj, At, Bt) do { __builtin_amdgcn_s_setprio(3); _Pragma("unroll") for (int m = 0; m < 4; ++m) _Pragma("unroll") for (int n = 0; n < 2; ++n) _Pragma("unroll") for (int k = 0; k < 2; ++k) \
;         acc[ai][bj][m][n] = __builtin_amdgcn_mfma_f32_16x16x32_bf16(Bt[n][k], At[m][k], acc[ai][bj][m][n], 0, 0, 0); __builtin_amdgcn_s_setprio(0); } while (0)
; #define PG8_WAIT_V(n) asm volatile("s_waitcnt vmcnt(" #n ")" ::: "memory")
; #define PG8_WAIT_L(n) asm volatile("s_waitcnt lgkmcnt(" #n ")" ::: "memory")
; #define PG8_BAR __builtin_amdgcn_s_barrier()
; #define PG8_SCHED __builtin_amdgcn_sched_barrier(0)
; template <class Epi, class Sched, bool ALIGN_EPI = false, bool SP2 = false>
; __device__ __forceinline__ void gemm_phase(LAS unsigned char* lds, const Gemm g, const Sched& S, const Epi& E) {
;     ...
;             PG8_WAIT_V(8); PG8_WAIT_L(0); PG8_BAR; PG8_MMA(0, 0, At, B0); PG8_MMA(0, 1, At, B1); PG8_BAR; PG8_SCHED;
;             PG8_LDA(At, 1, 1); PG8_STAGE(PG8_SB(1, 0), b3, voffB); PG8_STAGE(PG8_SB(1, 1), b3 + hsB, voffB); PG8_STAGE(PG8_SA(1, 0), a3, voffA);
;             PG8_WAIT_V(8); PG8_WAIT_L(0); PG8_BAR; PG8_MMA(1, 0, At, B0); PG8_MMA(1, 1, At, B1); PG8_BAR; PG8_SCHED;
;     ...
;         if constexpr (ALIGN_EPI) { if (wr == 0) PG8_BAR; }
	v_mfma_f32_16x16x32_bf16 v[128:131], v[112:115], v[192:195], v[128:131]
	v_mfma_f32_16x16x32_bf16 v[128:131], v[132:135], v[196:199], v[128:131]
	v_mfma_f32_16x16x32_bf16 v[124:127], v[136:139], v[192:195], v[124:127]
	v_mfma_f32_16x16x32_bf16 v[124:127], v[140:143], v[196:199], v[124:127]
	v_mfma_f32_16x16x32_bf16 v[108:111], v[112:115], v[206:209], v[108:111]
	v_mfma_f32_16x16x32_bf16 v[108:111], v[132:135], v[210:213], v[108:111]
	v_mfma_f32_16x16x32_bf16 v[104:107], v[136:139], v[206:209], v[104:107]
	v_mfma_f32_16x16x32_bf16 v[104:107], v[140:143], v[210:213], v[104:107]
	v_mfma_f32_16x16x32_bf16 v[92:95], v[112:115], v[214:217], v[92:95]
	v_mfma_f32_16x16x32_bf16 v[92:95], v[132:135], v[218:221], v[92:95]
	v_mfma_f32_16x16x32_bf16 v[88:91], v[136:139], v[214:217], v[88:91]
	v_mfma_f32_16x16x32_bf16 v[88:91], v[140:143], v[218:221], v[88:91]
	v_mfma_f32_16x16x32_bf16 v[76:79], v[112:115], v[222:225], v[76:79]
	v_mfma_f32_16x16x32_bf16 v[76:79], v[132:135], v[226:229], v[76:79]
	v_mfma_f32_16x16x32_bf16 v[72:75], v[136:139], v[222:225], v[72:75]
	v_mfma_f32_16x16x32_bf16 v[72:75], v[140:143], v[226:229], v[72:75]
	s_setprio 0
	s_setprio 2
	v_mfma_f32_16x16x32_bf16 v[120:123], v[144:147], v[192:195], v[120:123]
	v_mfma_f32_16x16x32_bf16 v[120:123], v[148:151], v[196:199], v[120:123]
	v_mfma_f32_16x16x32_bf16 v[116:119], v[184:187], v[192:195], v[116:119]
	v_mfma_f32_16x16x32_bf16 v[116:119], v[188:191], v[196:199], v[116:119]
	v_mfma_f32_16x16x32_bf16 v[100:103], v[144:147], v[206:209], v[100:103]
	v_mfma_f32_16x16x32_bf16 v[100:103], v[148:151], v[210:213], v[100:103]
	v_mfma_f32_16x16x32_bf16 v[96:99], v[184:187], v[206:209], v[96:99]
	v_mfma_f32_16x16x32_bf16 v[96:99], v[188:191], v[210:213], v[96:99]
	v_mfma_f32_16x16x32_bf16 v[84:87], v[144:147], v[214:217], v[84:87]
	v_mfma_f32_16x16x32_bf16 v[84:87], v[148:151], v[218:221], v[84:87]
	v_mfma_f32_16x16x32_bf16 v[80:83], v[184:187], v[214:217], v[80:83]
	v_mfma_f32_16x16x32_bf16 v[80:83], v[188:191], v[218:221], v[80:83]
	v_mfma_f32_16x16x32_bf16 v[68:71], v[144:147], v[222:225], v[68:71]
	v_mfma_f32_16x16x32_bf16 v[68:71], v[148:151], v[226:229], v[68:71]
	v_mfma_f32_16x16x32_bf16 v[64:67], v[184:187], v[222:225], v[64:67]
	s_setprio 3
	s_barrier
	v_mfma_f32_16x16x32_bf16 v[64:67], v[188:191], v[226:229], v[64:67]
	s_setprio 0
	s_add_i32 s26, s74, s31
	v_lshl_add_u64 v[200:201], v[200:201], 0, s[14:15]
	s_mov_b32 m0, s26
	ds_read_b128 v[192:195], v177 offset:49152
	ds_read_b128 v[196:199], v250 offset:49152
	ds_read_b128 v[206:209], v177 offset:51200
	ds_read_b128 v[210:213], v250 offset:51200
	ds_read_b128 v[214:217], v177 offset:53248
	ds_read_b128 v[218:221], v250 offset:53248
	ds_read_b128 v[222:225], v177 offset:55296
	ds_read_b128 v[226:229], v250 offset:55296
	global_load_lds_dwordx4 v[200:201], off
	s_add_i32 m0, s26, 0x2000
	s_add_u32 s24, s24, 0x41080
	v_lshl_add_u64 v[200:201], v[230:231], 0, s[14:15]
	s_addc_u32 s25, s25, 0
	s_add_i32 s26, s75, s31
	global_load_lds_dwordx4 v[200:201], off
	v_lshl_add_u64 v[200:201], s[24:25], 0, v[154:155]
	s_mov_b32 m0, s26
	s_nop 0
	global_load_lds_dwordx4 v[200:201], off
	v_lshl_add_u64 v[200:201], s[24:25], 0, v[158:159]
	s_add_i32 m0, s26, 0x2000
	s_nop 0
	global_load_lds_dwordx4 v[200:201], off
	s_waitcnt vmcnt(6)
	s_waitcnt lgkmcnt(0)
	s_setprio 2
	s_barrier
	v_mfma_f32_16x16x32_bf16 v[60:63], v[112:115], v[192:195], v[60:63]
	v_mfma_f32_16x16x32_bf16 v[60:63], v[132:135], v[196:199], v[60:63]
	v_mfma_f32_16x16x32_bf16 v[56:59], v[136:139], v[192:195], v[56:59]
	v_mfma_f32_16x16x32_bf16 v[56:59], v[140:143], v[196:199], v[56:59]
	v_mfma_f32_16x16x32_bf16 v[44:47], v[112:115], v[206:209], v[44:47]
	v_mfma_f32_16x16x32_bf16 v[44:47], v[132:135], v[210:213], v[44:47]
	v_mfma_f32_16x16x32_bf16 v[40:43], v[136:139], v[206:209], v[40:43]
	v_mfma_f32_16x16x32_bf16 v[40:43], v[140:143], v[210:213], v[40:43]
	v_mfma_f32_16x16x32_bf16 v[28:31], v[112:115], v[214:217], v[28:31]
	v_mfma_f32_16x16x32_bf16 v[28:31], v[132:135], v[218:221], v[28:31]
	v_mfma_f32_16x16x32_bf16 v[24:27], v[136:139], v[214:217], v[24:27]
	v_mfma_f32_16x16x32_bf16 v[24:27], v[140:143], v[218:221], v[24:27]
	v_mfma_f32_16x16x32_bf16 v[12:15], v[112:115], v[222:225], v[12:15]
	v_mfma_f32_16x16x32_bf16 v[12:15], v[132:135], v[226:229], v[12:15]
	v_mfma_f32_16x16x32_bf16 v[8:11], v[136:139], v[222:225], v[8:11]
	v_mfma_f32_16x16x32_bf16 v[8:11], v[140:143], v[226:229], v[8:11]
	s_setprio 0
	s_setprio 2
	v_mfma_f32_16x16x32_bf16 v[52:55], v[144:147], v[192:195], v[52:55]
	v_mfma_f32_16x16x32_bf16 v[52:55], v[148:151], v[196:199], v[52:55]
	v_mfma_f32_16x16x32_bf16 v[48:51], v[184:187], v[192:195], v[48:51]
	v_mfma_f32_16x16x32_bf16 v[48:51], v[188:191], v[196:199], v[48:51]
	v_mfma_f32_16x16x32_bf16 v[36:39], v[144:147], v[206:209], v[36:39]
	v_mfma_f32_16x16x32_bf16 v[36:39], v[148:151], v[210:213], v[36:39]
	v_mfma_f32_16x16x32_bf16 v[32:35], v[184:187], v[206:209], v[32:35]
	v_mfma_f32_16x16x32_bf16 v[32:35], v[188:191], v[210:213], v[32:35]
	v_mfma_f32_16x16x32_bf16 v[20:23], v[144:147], v[214:217], v[20:23]
	v_mfma_f32_16x16x32_bf16 v[20:23], v[148:151], v[218:221], v[20:23]
	v_mfma_f32_16x16x32_bf16 v[16:19], v[184:187], v[214:217], v[16:19]
	v_mfma_f32_16x16x32_bf16 v[16:19], v[188:191], v[218:221], v[16:19]
	v_mfma_f32_16x16x32_bf16 v[4:7], v[144:147], v[222:225], v[4:7]
	v_mfma_f32_16x16x32_bf16 v[4:7], v[148:151], v[226:229], v[4:7]
	v_mfma_f32_16x16x32_bf16 v[0:3], v[184:187], v[222:225], v[0:3]
	s_setprio 3
	s_barrier
	v_mfma_f32_16x16x32_bf16 v[0:3], v[188:191], v[226:229], v[0:3]
	s_setprio 0
	s_add_i32 s73, s73, 2
	s_add_u32 s4, s4, 0x100
	s_addc_u32 s5, s5, 0
	s_add_u32 s71, s71, 0x100
	s_addc_u32 s72, s72, 0
	s_cmp_gt_u32 s73, 61
	s_cbranch_scc0 .LBB0_309
	s_and_b64 vcc, exec, s[16:17]
	s_cbranch_vccz .LBB0_312
	s_barrier

; #define PG8_STAGE(bufoff, gbase, voff) do { _Pragma("unroll") for (int _i = 0; _i < 2; ++_i) \
;         __builtin_amdgcn_global_load_lds((const unsigned*)((const char*)(gbase) + (voff)[_i]), (LAS unsigned*)(lds + (bufoff) + ldsw + _i * 8192), 16, 0, 0); } while (0)
; #define PG8_LDA(dst, b, h) do { _Pragma("unroll") for (int m = 0; m < 4; ++m) _Pragma("unroll") for (int k = 0; k < 2; ++k) dst[m][k] = *(const LAS bf16x8*)(lds + PG8_SA(b, h) + aoff + m * 2048 + k * 1024); } while (0)
; #define PG8_LDB(dst, b, h) do { _Pragma("unroll") for (int n = 0; n < 2; ++n) _Pragma("unroll") for (int k = 0; k < 2; ++k) dst[n][k] = *(const LAS bf16x8*)(lds + PG8_SB(b, h) + boff + n * 2048 + k * 1024); } while (0)
; #define PG8_MMA(ai, bj, At, Bt) do { __builtin_amdgcn_s_setprio(3); _Pragma("unroll") for (int m = 0; m < 4; ++m) _Pragma("unroll") for (int n = 0; n < 2; ++n) _Pragma("unroll") for (int k = 0; k < 2; ++k) \
;         acc[ai][bj][m][n] = __builtin_amdgcn_mfma_f32_16x16x32_bf16(Bt[n][k], At[m][k], acc[ai][bj][m][n], 0, 0, 0); __builtin_amdgcn_s_setprio(0); } while (0)
; #define PG8_WAIT_V(n) asm volatile("s_waitcnt vmcnt(" #n ")" ::: "memory")
; #define PG8_WAIT_L(n) asm volatile("s_waitcnt lgkmcnt(" #n ")" ::: "memory")
; #define PG8_BAR __builtin_amdgcn_s_barrier()
; template <class Epi, class Sched, bool ALIGN_EPI = false, bool SP2 = false>
; __device__ __forceinline__ void gemm_phase(LAS unsigned char* lds, const Gemm g, const Sched& S, const Epi& E) {
;     ...
;             const bool last = (t == nt - 2);
;             const char* a1 = cA + (size_t)(t + 1) * kstep;
;             const char* a2 = last ? nA : cA + (size_t)(t + 2) * kstep; const char* b2 = last ? nB : cB + (size_t)(t + 2) * kstep;
;             const char* a3 = a2 + kstep; const char* b3 = b2 + kstep;
;             if (last && has_next) S.a_ready(nxt);
;             if constexpr (Epi::MID) { if (t == nt / 2) E.mid(acc, cur, wr, wc, fr, fq); }
;             if constexpr (SP2) {
;             PG8_LDB(B0, 0, 0); PG8_LDB(B1, 0, 1); PG8_SCHED; PG8_LDA(At, 0, 0); PG8_STAGE(PG8_SA(1, 1), a1 + hsA, voffA);
;             PG8_WAIT_V(8); PG8_WAIT_L(0); PG8_BAR; PG8_MMA(0, 0, At, B0); PG8_MMA(0, 1, At, B1); PG8_BAR; PG8_SCHED;
;             PG8_LDA(At, 0, 1); PG8_STAGE(PG8_SB(0, 0), b2, voffB); PG8_STAGE(PG8_SB(0, 1), b2 + hsB, voffB); PG8_STAGE(PG8_SA(0, 0), a2, voffA);
.LBB0_350:
	ds_read_b128 v[140:143], v149
	ds_read_b128 v[156:159], v251
	ds_read_b128 v[160:163], v149 offset:2048
	ds_read_b128 v[164:167], v251 offset:2048
	ds_read_b128 v[168:171], v150
	ds_read_b128 v[172:175], v252
	ds_read_b128 v[176:179], v150 offset:2048
	ds_read_b128 v[180:183], v252 offset:2048
	s_add_u32 s16, s14, 0xffbfc080
	s_addc_u32 s17, s15, -1
	s_cmpk_eq_i32 s50, 0xfc
	s_cselect_b32 s21, s5, s17
	s_cselect_b32 s20, s4, s16
	s_cselect_b32 s17, s13, s49
	s_cselect_b32 s16, s12, s48
	s_sub_u32 s100, s14, 0x404000
	s_subb_u32 s101, s15, 0
	v_lshl_add_u64 v[242:243], s[100:101], 0, v[128:129]
	s_mov_b32 m0, s33
	v_lshl_add_u64 v[244:245], s[100:101], 0, v[130:131]
	global_load_lds_dwordx4 v[242:243], off
	s_mov_b32 m0, s38
	s_nop 0
	global_load_lds_dwordx4 v[244:245], off
	v_lshl_add_u64 v[144:145], s[14:15], 0, v[132:133]
	s_add_i32 m0, s26, 0xc000
	ds_read_b128 v[184:187], v151
	ds_read_b128 v[188:191], v250
	ds_read_b128 v[192:195], v151 offset:2048
	ds_read_b128 v[196:199], v250 offset:2048
	ds_read_b128 v[200:203], v151 offset:4096
	ds_read_b128 v[204:207], v250 offset:4096
	ds_read_b128 v[208:211], v151 offset:6144
	ds_read_b128 v[212:215], v250 offset:6144
	global_load_lds_dwordx4 v[144:145], off
	v_lshl_add_u64 v[144:145], s[14:15], 0, v[134:135]
	s_add_i32 m0, s26, 0xe000
	s_nop 0
	global_load_lds_dwordx4 v[144:145], off
	s_waitcnt vmcnt(8)
	s_waitcnt lgkmcnt(0)
	s_setprio 2
	s_barrier
	v_mfma_f32_16x16x32_bf16 v[124:127], v[140:143], v[184:187], v[124:127]
	v_mfma_f32_16x16x32_bf16 v[124:127], v[156:159], v[188:191], v[124:127]
	v_mfma_f32_16x16x32_bf16 v[120:123], v[160:163], v[184:187], v[120:123]
	v_mfma_f32_16x16x32_bf16 v[120:123], v[164:167], v[188:191], v[120:123]
	v_mfma_f32_16x16x32_bf16 v[108:111], v[140:143], v[192:195], v[108:111]
	v_mfma_f32_16x16x32_bf16 v[108:111], v[156:159], v[196:199], v[108:111]
	v_mfma_f32_16x16x32_bf16 v[104:107], v[160:163], v[192:195], v[104:107]
	v_mfma_f32_16x16x32_bf16 v[104:107], v[164:167], v[196:199], v[104:107]
	v_mfma_f32_16x16x32_bf16 v[92:95], v[140:143], v[200:203], v[92:95]
	v_mfma_f32_16x16x32_bf16 v[92:95], v[156:159], v[204:207], v[92:95]
	v_mfma_f32_16x16x32_bf16 v[88:91], v[160:163], v[200:203], v[88:91]
	v_mfma_f32_16x16x32_bf16 v[88:91], v[164:167], v[204:207], v[88:91]
	v_mfma_f32_16x16x32_bf16 v[76:79], v[140:143], v[208:211], v[76:79]
	v_mfma_f32_16x16x32_bf16 v[76:79], v[156:159], v[212:215], v[76:79]
	v_mfma_f32_16x16x32_bf16 v[72:75], v[160:163], v[208:211], v[72:75]
	v_mfma_f32_16x16x32_bf16 v[72:75], v[164:167], v[212:215], v[72:75]
	s_setprio 0
	s_setprio 2
	v_mfma_f32_16x16x32_bf16 v[116:119], v[168:171], v[184:187], v[116:119]
	v_mfma_f32_16x16x32_bf16 v[116:119], v[172:175], v[188:191], v[116:119]
	v_mfma_f32_16x16x32_bf16 v[112:115], v[176:179], v[184:187], v[112:115]
	v_mfma_f32_16x16x32_bf16 v[112:115], v[180:183], v[188:191], v[112:115]
	v_mfma_f32_16x16x32_bf16 v[100:103], v[168:171], v[192:195], v[100:103]
	v_mfma_f32_16x16x32_bf16 v[100:103], v[172:175], v[196:199], v[100:103]
	v_mfma_f32_16x16x32_bf16 v[96:99], v[176:179], v[192:195], v[96:99]
	v_mfma_f32_16x16x32_bf16 v[96:99], v[180:183], v[196:199], v[96:99]
	v_mfma_f32_16x16x32_bf16 v[84:87], v[168:171], v[200:203], v[84:87]
	v_mfma_f32_16x16x32_bf16 v[84:87], v[172:175], v[204:207], v[84:87]
	v_mfma_f32_16x16x32_bf16 v[80:83], v[176:179], v[200:203], v[80:83]
	v_mfma_f32_16x16x32_bf16 v[80:83], v[180:183], v[204:207], v[80:83]
	v_mfma_f32_16x16x32_bf16 v[68:71], v[168:171], v[208:211], v[68:71]
	v_mfma_f32_16x16x32_bf16 v[68:71], v[172:175], v[212:215], v[68:71]
	s_setprio 3
	s_barrier
	v_mfma_f32_16x16x32_bf16 v[64:67], v[176:179], v[208:211], v[64:67]
	v_mfma_f32_16x16x32_bf16 v[64:67], v[180:183], v[212:215], v[64:67]
	s_setprio 0
	s_add_i32 s51, s41, s25
	v_lshl_add_u64 v[144:145], s[16:17], 0, v[128:129]
	s_mov_b32 m0, s51
	ds_read_b128 v[184:187], v151 offset:16384
	ds_read_b128 v[188:191], v250 offset:16384
	ds_read_b128 v[192:195], v151 offset:18432
	ds_read_b128 v[196:199], v250 offset:18432
	ds_read_b128 v[200:203], v151 offset:20480
	ds_read_b128 v[204:207], v250 offset:20480
	ds_read_b128 v[208:211], v151 offset:22528
	ds_read_b128 v[212:215], v250 offset:22528
	global_load_lds_dwordx4 v[144:145], off
	s_add_i32 m0, s51, 0x2000
	s_add_u32 s52, s16, 0x404000
	v_lshl_add_u64 v[216:217], s[16:17], 0, v[130:131]
	s_addc_u32 s53, s17, 0
	s_add_i32 s51, s42, s25
	global_load_lds_dwordx4 v[216:217], off
	v_lshl_add_u64 v[218:219], s[52:53], 0, v[128:129]
	s_mov_b32 m0, s51
	s_nop 0
	global_load_lds_dwordx4 v[218:219], off
	v_lshl_add_u64 v[218:219], s[52:53], 0, v[130:131]
	s_add_i32 m0, s51, 0x2000
	s_nop 0
	global_load_lds_dwordx4 v[218:219], off
	s_waitcnt vmcnt(6)
	s_waitcnt lgkmcnt(0)
	s_setprio 2
	s_barrier
; #define PG8_STAGE(bufoff, gbase, voff) do { _Pragma("unroll") for (int _i = 0; _i < 2; ++_i) \
;         __builtin_amdgcn_global_load_lds((const unsigned*)((const char*)(gbase) + (voff)[_i]), (LAS unsigned*)(lds + (bufoff) + ldsw + _i * 8192), 16, 0, 0); } while (0)
; #define PG8_LDA(dst, b, h) do { _Pragma("unroll") for (int m = 0; m < 4; ++m) _Pragma("unroll") for (int k = 0; k < 2; ++k) dst[m][k] = *(const LAS bf16x8*)(lds + PG8_SA(b, h) + aoff + m * 2048 + k * 1024); } while (0)
; #define PG8_LDB(dst, b, h) do { _Pragma("unroll") for (int n = 0; n < 2; ++n) _Pragma("unroll") for (int k = 0; k < 2; ++k) dst[n][k] = *(const LAS bf16x8*)(lds + PG8_SB(b, h) + boff + n * 2048 + k * 1024); } while (0)
; #define PG8_MMA(ai, bj, At, Bt) do { __builtin_amdgcn_s_setprio(3); _Pragma("unroll") for (int m = 0; m < 4; ++m) _Pragma("unroll") for (int n = 0; n < 2; ++n) _Pragma("unroll") for (int k = 0; k < 2; ++k) \
;         acc[ai][bj][m][n] = __builtin_amdgcn_mfma_f32_16x16x32_bf16(Bt[n][k], At[m][k], acc[ai][bj][m][n], 0, 0, 0); __builtin_amdgcn_s_setprio(0); } while (0)
; #define PG8_WAIT_V(n) asm volatile("s_waitcnt vmcnt(" #n ")" ::: "memory")
; #define PG8_WAIT_L(n) asm volatile("s_waitcnt lgkmcnt(" #n ")" ::: "memory")
; #define PG8_BAR __builtin_amdgcn_s_barrier()
; #define PG8_SCHED __builtin_amdgcn_sched_barrier(0)
; template <class Epi, class Sched, bool ALIGN_EPI = false, bool SP2 = false>
; __device__ __forceinline__ void gemm_phase(LAS unsigned char* lds, const Gemm g, const Sched& S, const Epi& E) {
;     ...
;             PG8_WAIT_V(8); PG8_WAIT_L(0); PG8_BAR; PG8_MMA(1, 0, At, B0); PG8_MMA(1, 1, At, B1); PG8_BAR; PG8_SCHED;
;             PG8_LDB(B0, 1, 0); PG8_LDB(B1, 1, 1); PG8_SCHED; PG8_LDA(At, 1, 0); PG8_STAGE(PG8_SA(0, 1), a2 + hsA, voffA);
	v_mfma_f32_16x16x32_bf16 v[60:63], v[140:143], v[184:187], v[60:63]
	v_mfma_f32_16x16x32_bf16 v[60:63], v[156:159], v[188:191], v[60:63]
	v_mfma_f32_16x16x32_bf16 v[56:59], v[160:163], v[184:187], v[56:59]
	v_mfma_f32_16x16x32_bf16 v[56:59], v[164:167], v[188:191], v[56:59]
	v_mfma_f32_16x16x32_bf16 v[44:47], v[140:143], v[192:195], v[44:47]
	v_mfma_f32_16x16x32_bf16 v[44:47], v[156:159], v[196:199], v[44:47]
	v_mfma_f32_16x16x32_bf16 v[40:43], v[160:163], v[192:195], v[40:43]
	v_mfma_f32_16x16x32_bf16 v[40:43], v[164:167], v[196:199], v[40:43]
	v_mfma_f32_16x16x32_bf16 v[28:31], v[140:143], v[200:203], v[28:31]
	v_mfma_f32_16x16x32_bf16 v[28:31], v[156:159], v[204:207], v[28:31]
	v_mfma_f32_16x16x32_bf16 v[24:27], v[160:163], v[200:203], v[24:27]
	v_mfma_f32_16x16x32_bf16 v[24:27], v[164:167], v[204:207], v[24:27]
	v_mfma_f32_16x16x32_bf16 v[12:15], v[140:143], v[208:211], v[12:15]
	v_mfma_f32_16x16x32_bf16 v[12:15], v[156:159], v[212:215], v[12:15]
	v_mfma_f32_16x16x32_bf16 v[8:11], v[160:163], v[208:211], v[8:11]
	v_mfma_f32_16x16x32_bf16 v[8:11], v[164:167], v[212:215], v[8:11]
	s_setprio 0
	s_setprio 2
	v_mfma_f32_16x16x32_bf16 v[52:55], v[168:171], v[184:187], v[52:55]
	v_mfma_f32_16x16x32_bf16 v[52:55], v[172:175], v[188:191], v[52:55]
	v_mfma_f32_16x16x32_bf16 v[48:51], v[176:179], v[184:187], v[48:51]
	v_mfma_f32_16x16x32_bf16 v[48:51], v[180:183], v[188:191], v[48:51]
	v_mfma_f32_16x16x32_bf16 v[36:39], v[168:171], v[192:195], v[36:39]
	v_mfma_f32_16x16x32_bf16 v[36:39], v[172:175], v[196:199], v[36:39]
	v_mfma_f32_16x16x32_bf16 v[32:35], v[176:179], v[192:195], v[32:35]
	v_mfma_f32_16x16x32_bf16 v[32:35], v[180:183], v[196:199], v[32:35]
	v_mfma_f32_16x16x32_bf16 v[20:23], v[168:171], v[200:203], v[20:23]
	v_mfma_f32_16x16x32_bf16 v[20:23], v[172:175], v[204:207], v[20:23]
	v_mfma_f32_16x16x32_bf16 v[16:19], v[176:179], v[200:203], v[16:19]
	v_mfma_f32_16x16x32_bf16 v[16:19], v[180:183], v[204:207], v[16:19]
	v_mfma_f32_16x16x32_bf16 v[4:7], v[168:171], v[208:211], v[4:7]
	v_mfma_f32_16x16x32_bf16 v[4:7], v[172:175], v[212:215], v[4:7]
	s_setprio 3
	s_barrier
	v_mfma_f32_16x16x32_bf16 v[0:3], v[176:179], v[208:211], v[0:3]
	v_mfma_f32_16x16x32_bf16 v[0:3], v[180:183], v[212:215], v[0:3]
	s_setprio 0
	s_add_i32 s51, 0, 0x18000
	v_add_u32_e32 v155, s51, v146
	v_xor_b32_e32 v253, 64, v155
	s_add_i32 s52, 0, 0x1c000
	ds_read_b128 v[140:143], v155
	ds_read_b128 v[156:159], v253
	ds_read_b128 v[160:163], v155 offset:2048
	ds_read_b128 v[164:167], v253 offset:2048
	v_add_u32_e32 v155, s52, v146
	v_xor_b32_e32 v253, 64, v155
	ds_read_b128 v[168:171], v155
	ds_read_b128 v[172:175], v253
	ds_read_b128 v[176:179], v155 offset:2048
	ds_read_b128 v[180:183], v253 offset:2048
	v_lshl_add_u64 v[242:243], s[20:21], 0, v[128:129]
	s_mov_b32 m0, s26
	v_lshl_add_u64 v[244:245], s[20:21], 0, v[130:131]
	global_load_lds_dwordx4 v[242:243], off
	s_mov_b32 m0, s27
	s_nop 0
	global_load_lds_dwordx4 v[244:245], off
	s_add_u32 s20, s20, 0x404000
	s_addc_u32 s21, s21, 0
	s_mov_b32 m0, s30
	v_lshl_add_u64 v[222:223], s[20:21], 0, v[128:129]
	ds_read_b128 v[184:187], v151 offset:32768
	ds_read_b128 v[188:191], v250 offset:32768
	ds_read_b128 v[192:195], v151 offset:34816
	ds_read_b128 v[196:199], v250 offset:34816
	ds_read_b128 v[200:203], v151 offset:36864
	ds_read_b128 v[204:207], v250 offset:36864
	ds_read_b128 v[208:211], v151 offset:38912
	ds_read_b128 v[212:215], v250 offset:38912
	global_load_lds_dwordx4 v[222:223], off
	v_lshl_add_u64 v[222:223], s[20:21], 0, v[130:131]
	s_mov_b32 m0, s31
	s_nop 0
	global_load_lds_dwordx4 v[222:223], off
	s_waitcnt vmcnt(8)
	s_waitcnt lgkmcnt(0)
	s_setprio 2
	s_barrier
; #define PG8_STAGE(bufoff, gbase, voff) do { _Pragma("unroll") for (int _i = 0; _i < 2; ++_i) \
;         __builtin_amdgcn_global_load_lds((const unsigned*)((const char*)(gbase) + (voff)[_i]), (LAS unsigned*)(lds + (bufoff) + ldsw + _i * 8192), 16, 0, 0); } while (0)
; #define PG8_LDA(dst, b, h) do { _Pragma("unroll") for (int m = 0; m < 4; ++m) _Pragma("unroll") for (int k = 0; k < 2; ++k) dst[m][k] = *(const LAS bf16x8*)(lds + PG8_SA(b, h) + aoff + m * 2048 + k * 1024); } while (0)
; #define PG8_MMA(ai, bj, At, Bt) do { __builtin_amdgcn_s_setprio(3); _Pragma("unroll") for (int m = 0; m < 4; ++m) _Pragma("unroll") for (int n = 0; n < 2; ++n) _Pragma("unroll") for (int k = 0; k < 2; ++k) \
;         acc[ai][bj][m][n] = __builtin_amdgcn_mfma_f32_16x16x32_bf16(Bt[n][k], At[m][k], acc[ai][bj][m][n], 0, 0, 0); __builtin_amdgcn_s_setprio(0); } while (0)
; #define PG8_WAIT_V(n) asm volatile("s_waitcnt vmcnt(" #n ")" ::: "memory")
; #define PG8_WAIT_L(n) asm volatile("s_waitcnt lgkmcnt(" #n ")" ::: "memory")
; #define PG8_BAR __builtin_amdgcn_s_barrier()
; #define PG8_SCHED __builtin_amdgcn_sched_barrier(0)
; template <class Epi, class Sched, bool ALIGN_EPI = false, bool SP2 = false>
; __device__ __forceinline__ void gemm_phase(LAS unsigned char* lds, const Gemm g, const Sched& S, const Epi& E) {
;     ...
;             PG8_WAIT_V(8); PG8_WAIT_L(0); PG8_BAR; PG8_MMA(0, 0, At, B0); PG8_MMA(0, 1, At, B1); PG8_BAR; PG8_SCHED;
;             PG8_LDA(At, 1, 1); PG8_STAGE(PG8_SB(1, 0), b3, voffB); PG8_STAGE(PG8_SB(1, 1), b3 + hsB, voffB); PG8_STAGE(PG8_SA(1, 0), a3, voffA);
;             PG8_WAIT_V(8); PG8_WAIT_L(0); PG8_BAR; PG8_MMA(1, 0, At, B0); PG8_MMA(1, 1, At, B1); PG8_BAR; PG8_SCHED;
;     ...
;         if constexpr (ALIGN_EPI) { if (wr == 0) PG8_BAR; }
	v_mfma_f32_16x16x32_bf16 v[124:127], v[140:143], v[184:187], v[124:127]
	v_mfma_f32_16x16x32_bf16 v[124:127], v[156:159], v[188:191], v[124:127]
	v_mfma_f32_16x16x32_bf16 v[120:123], v[160:163], v[184:187], v[120:123]
	v_mfma_f32_16x16x32_bf16 v[120:123], v[164:167], v[188:191], v[120:123]
	v_mfma_f32_16x16x32_bf16 v[108:111], v[140:143], v[192:195], v[108:111]
	v_mfma_f32_16x16x32_bf16 v[108:111], v[156:159], v[196:199], v[108:111]
	v_mfma_f32_16x16x32_bf16 v[104:107], v[160:163], v[192:195], v[104:107]
	v_mfma_f32_16x16x32_bf16 v[104:107], v[164:167], v[196:199], v[104:107]
	v_mfma_f32_16x16x32_bf16 v[92:95], v[140:143], v[200:203], v[92:95]
	v_mfma_f32_16x16x32_bf16 v[92:95], v[156:159], v[204:207], v[92:95]
	v_mfma_f32_16x16x32_bf16 v[88:91], v[160:163], v[200:203], v[88:91]
	v_mfma_f32_16x16x32_bf16 v[88:91], v[164:167], v[204:207], v[88:91]
	v_mfma_f32_16x16x32_bf16 v[76:79], v[140:143], v[208:211], v[76:79]
	v_mfma_f32_16x16x32_bf16 v[76:79], v[156:159], v[212:215], v[76:79]
	v_mfma_f32_16x16x32_bf16 v[72:75], v[160:163], v[208:211], v[72:75]
	v_mfma_f32_16x16x32_bf16 v[72:75], v[164:167], v[212:215], v[72:75]
	s_setprio 0
	s_setprio 2
	v_mfma_f32_16x16x32_bf16 v[116:119], v[168:171], v[184:187], v[116:119]
	v_mfma_f32_16x16x32_bf16 v[116:119], v[172:175], v[188:191], v[116:119]
	v_mfma_f32_16x16x32_bf16 v[112:115], v[176:179], v[184:187], v[112:115]
	v_mfma_f32_16x16x32_bf16 v[112:115], v[180:183], v[188:191], v[112:115]
	v_mfma_f32_16x16x32_bf16 v[100:103], v[168:171], v[192:195], v[100:103]
	v_mfma_f32_16x16x32_bf16 v[100:103], v[172:175], v[196:199], v[100:103]
	v_mfma_f32_16x16x32_bf16 v[96:99], v[176:179], v[192:195], v[96:99]
	v_mfma_f32_16x16x32_bf16 v[96:99], v[180:183], v[196:199], v[96:99]
	v_mfma_f32_16x16x32_bf16 v[84:87], v[168:171], v[200:203], v[84:87]
	v_mfma_f32_16x16x32_bf16 v[84:87], v[172:175], v[204:207], v[84:87]
	v_mfma_f32_16x16x32_bf16 v[80:83], v[176:179], v[200:203], v[80:83]
	v_mfma_f32_16x16x32_bf16 v[80:83], v[180:183], v[204:207], v[80:83]
	v_mfma_f32_16x16x32_bf16 v[68:71], v[168:171], v[208:211], v[68:71]
	v_mfma_f32_16x16x32_bf16 v[68:71], v[172:175], v[212:215], v[68:71]
	s_setprio 3
	s_barrier
	v_mfma_f32_16x16x32_bf16 v[64:67], v[176:179], v[208:211], v[64:67]
	v_mfma_f32_16x16x32_bf16 v[64:67], v[180:183], v[212:215], v[64:67]
	s_setprio 0
	s_add_i32 s20, s51, s25
	v_lshl_add_u64 v[144:145], v[144:145], 0, s[8:9]
	s_mov_b32 m0, s20
	ds_read_b128 v[184:187], v151 offset:49152
	ds_read_b128 v[188:191], v250 offset:49152
	ds_read_b128 v[192:195], v151 offset:51200
	ds_read_b128 v[196:199], v250 offset:51200
	ds_read_b128 v[200:203], v151 offset:53248
	ds_read_b128 v[204:207], v250 offset:53248
	ds_read_b128 v[208:211], v151 offset:55296
	ds_read_b128 v[212:215], v250 offset:55296
	global_load_lds_dwordx4 v[144:145], off
	s_add_i32 m0, s20, 0x2000
	s_add_u32 s16, s16, 0x404080
	v_lshl_add_u64 v[144:145], v[216:217], 0, s[8:9]
	s_addc_u32 s17, s17, 0
	s_add_i32 s20, s52, s25
	global_load_lds_dwordx4 v[144:145], off
	v_lshl_add_u64 v[144:145], s[16:17], 0, v[128:129]
	s_mov_b32 m0, s20
	s_nop 0
	global_load_lds_dwordx4 v[144:145], off
	v_lshl_add_u64 v[144:145], s[16:17], 0, v[130:131]
	s_add_i32 m0, s20, 0x2000
	s_nop 0
	global_load_lds_dwordx4 v[144:145], off
	s_waitcnt vmcnt(6)
	s_waitcnt lgkmcnt(0)
	s_setprio 2
	s_barrier
	v_mfma_f32_16x16x32_bf16 v[60:63], v[140:143], v[184:187], v[60:63]
	v_mfma_f32_16x16x32_bf16 v[60:63], v[156:159], v[188:191], v[60:63]
	v_mfma_f32_16x16x32_bf16 v[56:59], v[160:163], v[184:187], v[56:59]
	v_mfma_f32_16x16x32_bf16 v[56:59], v[164:167], v[188:191], v[56:59]
	v_mfma_f32_16x16x32_bf16 v[44:47], v[140:143], v[192:195], v[44:47]
	v_mfma_f32_16x16x32_bf16 v[44:47], v[156:159], v[196:199], v[44:47]
	v_mfma_f32_16x16x32_bf16 v[40:43], v[160:163], v[192:195], v[40:43]
	v_mfma_f32_16x16x32_bf16 v[40:43], v[164:167], v[196:199], v[40:43]
	v_mfma_f32_16x16x32_bf16 v[28:31], v[140:143], v[200:203], v[28:31]
	v_mfma_f32_16x16x32_bf16 v[28:31], v[156:159], v[204:207], v[28:31]
	v_mfma_f32_16x16x32_bf16 v[24:27], v[160:163], v[200:203], v[24:27]
	v_mfma_f32_16x16x32_bf16 v[24:27], v[164:167], v[204:207], v[24:27]
	v_mfma_f32_16x16x32_bf16 v[12:15], v[140:143], v[208:211], v[12:15]
	v_mfma_f32_16x16x32_bf16 v[12:15], v[156:159], v[212:215], v[12:15]
	v_mfma_f32_16x16x32_bf16 v[8:11], v[160:163], v[208:211], v[8:11]
	v_mfma_f32_16x16x32_bf16 v[8:11], v[164:167], v[212:215], v[8:11]
	s_setprio 0
	s_setprio 2
	v_mfma_f32_16x16x32_bf16 v[52:55], v[168:171], v[184:187], v[52:55]
	v_mfma_f32_16x16x32_bf16 v[52:55], v[172:175], v[188:191], v[52:55]
	v_mfma_f32_16x16x32_bf16 v[48:51], v[176:179], v[184:187], v[48:51]
	v_mfma_f32_16x16x32_bf16 v[48:51], v[180:183], v[188:191], v[48:51]
	v_mfma_f32_16x16x32_bf16 v[36:39], v[168:171], v[192:195], v[36:39]
	v_mfma_f32_16x16x32_bf16 v[36:39], v[172:175], v[196:199], v[36:39]
	v_mfma_f32_16x16x32_bf16 v[32:35], v[176:179], v[192:195], v[32:35]
	v_mfma_f32_16x16x32_bf16 v[32:35], v[180:183], v[196:199], v[32:35]
	v_mfma_f32_16x16x32_bf16 v[20:23], v[168:171], v[200:203], v[20:23]
	v_mfma_f32_16x16x32_bf16 v[20:23], v[172:175], v[204:207], v[20:23]
	v_mfma_f32_16x16x32_bf16 v[16:19], v[176:179], v[200:203], v[16:19]
	v_mfma_f32_16x16x32_bf16 v[16:19], v[180:183], v[204:207], v[16:19]
	v_mfma_f32_16x16x32_bf16 v[4:7], v[168:171], v[208:211], v[4:7]
	v_mfma_f32_16x16x32_bf16 v[4:7], v[172:175], v[212:215], v[4:7]
	s_setprio 3
	s_barrier
	v_mfma_f32_16x16x32_bf16 v[0:3], v[176:179], v[208:211], v[0:3]
	v_mfma_f32_16x16x32_bf16 v[0:3], v[180:183], v[212:215], v[0:3]
	s_setprio 0
	s_add_i32 s50, s50, 2
	s_add_u32 s14, s14, 0x100
	s_addc_u32 s15, s15, 0
	s_add_u32 s48, s48, 0x100
	s_addc_u32 s49, s49, 0
	s_cmpk_gt_u32 s50, 0xfd
	s_cbranch_scc0 .LBB0_350
	s_and_b64 vcc, exec, s[10:11]
	s_cbranch_vccz .LBB0_353
	s_barrier
